# FFN gate/up unrolled K blocks: same rotation across the slice barrier (last 4 MFMAs behind the next slice's first reads), LDS writes in the first half, refill loads under k-steps 2-3
# baseline (speedup 1.0000x reference)
; DI bf16x8 cat8(s16x4 lo, s16x4 hi) { return __builtin_shufflevector(lo, hi, 0, 1, 2, 3, 4, 5, 6, 7); }
; template <int BM, class Epi>
; DI void gemm_tile(const bf16_t* __restrict__ A, int lda, const bf16_t* __restrict__ B, int ldb, int K, int row0, int col0, const Epi& epi, char* smem) {
;     ...
;     const bf16_t* ag = A + (size_t)(row0 + (tid >> 3)) * lda + (tid & 7) * 8;
;     const bf16_t* bg = B + (size_t)(tid >> 5) * ldb + col0 + (tid & 31) * 8;
;     const int aw = (tid >> 3) * GA_S + (tid & 7) * 16, bw = BM * GA_S + (tid >> 5) * GB_S + (tid & 31) * 16;
;     const int nk = K >> 6;
;     const int xoff = (wm * (BM / 2) + l31) * GA_S + hh * 16;
;     const int woff = BM * GA_S + (hh * 8 + q) * GB_S + (wn * 64 + nblk * 16 + 4 * p) * 2;
; #pragma unroll
;     for (int i = 0; i < NA_; ++i) ra[i] = *(const u32x4*)(ag + (size_t)(64 * i) * lda);
; #pragma unroll
;     for (int i = 0; i < 4; ++i) rb[i] = *(const u32x4*)(bg + (size_t)(16 * i) * ldb);
;     __syncthreads();
; #pragma unroll
;     for (int i = 0; i < NA_; ++i) *(u32x4*)(smem + aw + 64 * i * GA_S) = ra[i];
; #pragma unroll
;     for (int i = 0; i < 4; ++i) *(u32x4*)(smem + bw + 16 * i * GB_S) = rb[i];
;     if (nk > 1) {
; #pragma unroll
;         for (int i = 0; i < NA_; ++i) ra[i] = *(const u32x4*)(ag + 64 + (size_t)(64 * i) * lda);
; #pragma unroll
;         for (int i = 0; i < 4; ++i) rb[i] = *(const u32x4*)(bg + (size_t)(64 + 16 * i) * ldb);
;     }
;     __syncthreads();
;     for (int kt = 0; kt < nk; ++kt) {
;         const char* cur = smem + (kt & 1) * GSTAGE;
;         char* nxt = smem + ((kt & 1) ^ 1) * GSTAGE;
;         const bool w1 = kt + 1 < nk, l2 = kt + 2 < nk;
;         const bf16_t* a2 = ag + (size_t)(kt + 2) * 64; const bf16_t* b2 = bg + (size_t)(kt + 2) * 64 * ldb;
; #pragma unroll
;         for (int s = 0; s < 4; ++s) {
;             bf16x8 xf[MI], wf[2];
; #pragma unroll
;             for (int mi = 0; mi < MI; ++mi) xf[mi] = *(const bf16x8*)(cur + xoff + mi * 32 * GA_S + s * 32);
; #pragma unroll
;             for (int ni = 0; ni < 2; ++ni) {
;                 const char* wp = cur + woff + s * 16 * GB_S + ni * 64;
;                 wf[ni] = cat8(tr_read(wp), tr_read(wp + 4 * GB_S));
;             }
; #pragma unroll
;             for (int mi = 0; mi < MI; ++mi)
; #pragma unroll
;                 for (int ni = 0; ni < 2; ++ni) acc[mi][ni] = mfma32(wf[ni], xf[mi], acc[mi][ni]);
.LBB0_1505:
	s_lshr_b32 s0, s11, 2
	s_add_i32 s1, s0, s6
	s_lshl_b32 s6, s11, 3
	s_lshl_b32 s0, s7, 5
	s_and_b32 s6, s6, 24
	s_or_b32 s0, s0, s6
	s_or_b32 s0, s0, s9
	v_mov_b32_e32 v177, v194
	s_lshl_b32 s0, s0, 8
	v_readlane_b32 s12, v253, 5
	v_ashrrev_i32_e32 v42, 3, v177
	v_add_u32_e32 v0, s0, v42
	v_ashrrev_i32_e32 v1, 31, v0
	v_lshlrev_b64 v[0:1], 11, v[0:1]
	v_readlane_b32 s13, v253, 6
	v_lshlrev_b32_e32 v2, 4, v177
	v_and_b32_e32 v172, 0x70, v2
	v_lshl_add_u64 v[0:1], s[12:13], 0, v[0:1]
	v_lshl_add_u64 v[136:137], v[0:1], 0, v[172:173]
	v_add_co_u32_e32 v138, vcc, s17, v136
	s_lshl_b32 s6, s1, 8
	s_nop 0
	v_addc_co_u32_e32 v139, vcc, 0, v137, vcc
	s_mov_b32 s1, 0x40000
	v_ashrrev_i32_e32 v43, 5, v177
	v_add_co_u32_e32 v140, vcc, s1, v136
	v_and_b32_e32 v178, 31, v177
	v_mad_i64_i32 v[0:1], s[12:13], v43, s33, v[174:175]
	s_ashr_i32 s7, s6, 31
	v_addc_co_u32_e32 v141, vcc, 0, v137, vcc
	s_mov_b32 s1, 0x60000
	v_lshl_add_u64 v[0:1], s[6:7], 1, v[0:1]
	v_lshlrev_b32_e32 v40, 4, v178
	v_mov_b32_e32 v41, v173
	v_add_co_u32_e32 v142, vcc, s1, v136
	v_lshl_add_u64 v[144:145], v[0:1], 0, v[40:41]
	s_nop 0
	v_addc_co_u32_e32 v143, vcc, 0, v137, vcc
	v_add_co_u32_e32 v20, vcc, s21, v144
	global_load_dwordx4 v[0:3], v[138:139], off
	global_load_dwordx4 v[4:7], v[140:141], off
	v_addc_co_u32_e32 v21, vcc, 0, v145, vcc
	v_add_co_u32_e32 v24, vcc, s18, v144
	global_load_dwordx4 v[8:11], v[136:137], off
	global_load_dwordx4 v[12:15], v[144:145], off
	v_addc_co_u32_e32 v25, vcc, 0, v145, vcc
	s_waitcnt vmcnt(5)
	v_add_co_u32_e32 v28, vcc, s37, v144
	global_load_dwordx4 v[16:19], v[142:143], off
	s_nop 0
	global_load_dwordx4 v[20:23], v[20:21], off
	v_addc_co_u32_e32 v29, vcc, 0, v145, vcc
	global_load_dwordx4 v[24:27], v[24:25], off
	s_nop 0
	global_load_dwordx4 v[28:31], v[28:29], off
	s_mov_b32 s1, 0xb0000
	v_add_co_u32_e32 v36, vcc, s1, v144
	s_waitcnt vmcnt(63) expcnt(7) lgkmcnt(15)
	s_barrier
	global_load_dwordx4 v[32:35], v[136:137], off offset:128
	v_addc_co_u32_e32 v37, vcc, 0, v145, vcc
	global_load_dwordx4 v[36:39], v[36:37], off
	v_bfe_u32 v44, v177, 5, 1
	v_lshrrev_b32_e32 v41, 2, v177
	v_ashrrev_i32_e32 v45, 1, v177
	v_and_b32_e32 v46, 0xd0, v177
	v_lshlrev_b32_e32 v47, 2, v177
	v_lshlrev_b32_e32 v176, 3, v44
	s_movk_i32 s7, 0x90
	v_and_b32_e32 v179, 0xffffff80, v45
	v_and_or_b32 v45, v47, 12, v46
	v_and_or_b32 v47, v41, 3, v176
	v_mad_u64_u32 v[40:41], s[12:13], v43, s16, v[40:41]
	v_mad_u64_u32 v[42:43], s[12:13], v42, s7, v[172:173]
	v_add_u32_e32 v151, 0, v42
	v_add_u32_e32 v152, 0, v40
	s_mov_b32 s1, 0x108000
	v_or_b32_e32 v46, v179, v178
	v_mul_u32_u24_e32 v153, 0x240, v47
	v_lshlrev_b32_e32 v170, 1, v45
	v_mul_lo_u32 v171, v46, s7
	v_lshlrev_b32_e32 v172, 4, v44
	v_add3_u32 v149, 0, v153, v170
	v_add3_u32 v148, 0, v171, v172
	v_add_u32_e32 v150, 0x9000, v149
	s_add_i32 s8, s8, s10
	s_waitcnt vmcnt(7)
	ds_write_b128 v151, v[8:11]
	ds_write_b128 v151, v[0:3] offset:9216
	ds_write_b128 v151, v[4:7] offset:18432
	s_waitcnt vmcnt(5)
	ds_write_b128 v151, v[16:19] offset:27648
	ds_write_b128 v152, v[12:15] offset:36864
	s_waitcnt vmcnt(4)
	ds_write_b128 v152, v[20:23] offset:46080
	s_waitcnt vmcnt(3)
	ds_write_b128 v152, v[24:27] offset:55296
	s_waitcnt vmcnt(2)
	ds_write_b128 v152, v[28:31] offset:64512
	v_add_co_u32_e32 v0, vcc, s38, v144
	global_load_dwordx4 v[128:131], v[138:139], off offset:128
	global_load_dwordx4 v[132:135], v[140:141], off offset:128
	global_load_dwordx4 v[154:157], v[142:143], off offset:128
	v_addc_co_u32_e32 v1, vcc, 0, v145, vcc
	global_load_dwordx4 v[158:161], v[0:1], off
	v_add_co_u32_e32 v0, vcc, s1, v144
	s_add_i32 s1, 0, 0x12000
	s_nop 0
	v_addc_co_u32_e32 v1, vcc, 0, v145, vcc
	v_add_co_u32_e32 v2, vcc, s39, v144
	v_add_u32_e32 v147, s1, v42
	s_nop 0
	v_addc_co_u32_e32 v3, vcc, 0, v145, vcc
	global_load_dwordx4 v[162:165], v[0:1], off
	global_load_dwordx4 v[166:169], v[2:3], off
	s_waitcnt lgkmcnt(0)
	s_barrier
	ds_read_b64_tr_b16 v[0:1], v149 offset:36864
	ds_read_b64_tr_b16 v[2:3], v149 offset:39168
	ds_read_b128 v[4:7], v148
	ds_read_b128 v[8:11], v148 offset:4608
	ds_read_b64_tr_b16 v[18:19], v149 offset:39232
	ds_read_b64_tr_b16 v[16:17], v149 offset:36928
	s_waitcnt lgkmcnt(3)
	v_mfma_f32_32x32x16_bf16 v[112:127], v[0:3], v[4:7], 0
	ds_read_b128 v[12:15], v148 offset:9216
	ds_read_b128 v[20:23], v148 offset:13824
	v_add_u32_e32 v146, s1, v40
	s_waitcnt vmcnt(7)
	ds_write_b128 v147, v[32:35]
	s_waitcnt vmcnt(6)
	ds_write_b128 v146, v[36:39] offset:36864
	v_add3_u32 v172, s1, v171, v172
	s_cmpk_gt_i32 s8, 0x15f
	s_waitcnt lgkmcnt(4)
	v_mfma_f32_32x32x16_bf16 v[96:111], v[16:19], v[4:7], 0
	ds_read_b64_tr_b16 v[24:25], v149 offset:46080
	ds_read_b64_tr_b16 v[26:27], v149 offset:48384
	ds_read_b128 v[4:7], v148 offset:32
	ds_read_b128 v[28:31], v148 offset:4640
	ds_read_b64_tr_b16 v[182:183], v149 offset:48448
	ds_read_b64_tr_b16 v[180:181], v149 offset:46144
	s_waitcnt lgkmcnt(9)
	v_mfma_f32_32x32x16_bf16 v[32:47], v[0:3], v[12:15], 0
	v_mfma_f32_32x32x16_bf16 v[48:63], v[16:19], v[12:15], 0
	s_waitcnt lgkmcnt(3)
	v_mfma_f32_32x32x16_bf16 v[112:127], v[24:27], v[4:7], v[112:127]
	s_waitcnt lgkmcnt(0)
	v_mfma_f32_32x32x16_bf16 v[96:111], v[180:183], v[4:7], v[96:111]
	ds_read_b128 v[4:7], v148 offset:9248
	ds_read_b128 v[184:187], v148 offset:13856
	s_waitcnt vmcnt(5)
	ds_write_b128 v147, v[128:131] offset:9216
	s_waitcnt vmcnt(2)
	ds_write_b128 v146, v[158:161] offset:46080
	v_mfma_f32_32x32x16_bf16 v[80:95], v[0:3], v[8:11], 0
	v_mfma_f32_32x32x16_bf16 v[64:79], v[16:19], v[8:11], 0
	s_waitcnt lgkmcnt(3)
; DI f32x16 mfma32(bf16x8 a, bf16x8 b, f32x16 c) { return __builtin_amdgcn_mfma_f32_32x32x16_bf16(a, b, c, 0, 0, 0); }
; DI s16x4 tr_read(const char* p) { bfx4 r = __builtin_amdgcn_ds_read_tr16_b64_v4bf16((LDS_AS bfx4*)p); return __builtin_bit_cast(s16x4, r); }
; DI bf16x8 cat8(s16x4 lo, s16x4 hi) { return __builtin_shufflevector(lo, hi, 0, 1, 2, 3, 4, 5, 6, 7); }
; template <int BM, class Epi>
; DI void gemm_tile(const bf16_t* __restrict__ A, int lda, const bf16_t* __restrict__ B, int ldb, int K, int row0, int col0, const Epi& epi, char* smem) {
;     ...
;     for (int kt = 0; kt < nk; ++kt) {
;         const char* cur = smem + (kt & 1) * GSTAGE;
;         char* nxt = smem + ((kt & 1) ^ 1) * GSTAGE;
;         const bool w1 = kt + 1 < nk, l2 = kt + 2 < nk;
;         const bf16_t* a2 = ag + (size_t)(kt + 2) * 64; const bf16_t* b2 = bg + (size_t)(kt + 2) * 64 * ldb;
; #pragma unroll
;         for (int s = 0; s < 4; ++s) {
;             bf16x8 xf[MI], wf[2];
; #pragma unroll
;             for (int mi = 0; mi < MI; ++mi) xf[mi] = *(const bf16x8*)(cur + xoff + mi * 32 * GA_S + s * 32);
; #pragma unroll
;             for (int ni = 0; ni < 2; ++ni) {
;                 const char* wp = cur + woff + s * 16 * GB_S + ni * 64;
;                 wf[ni] = cat8(tr_read(wp), tr_read(wp + 4 * GB_S));
;             }
; #pragma unroll
;             for (int mi = 0; mi < MI; ++mi)
; #pragma unroll
;                 for (int ni = 0; ni < 2; ++ni) acc[mi][ni] = mfma32(wf[ni], xf[mi], acc[mi][ni]);
;             if (w1) {
;                 if (s < NA_) *(u32x4*)(nxt + aw + 64 * s * GA_S) = ra[s];
;                 *(u32x4*)(nxt + bw + 16 * s * GB_S) = rb[s];
;             }
;             if (l2) {
;                 if (s < NA_) ra[s] = *(const u32x4*)(a2 + (size_t)(64 * s) * lda);
;                 rb[s] = *(const u32x4*)(b2 + (size_t)(16 * s) * ldb);
;             }
;         }
	v_mfma_f32_32x32x16_bf16 v[32:47], v[24:27], v[4:7], v[32:47]
	v_mfma_f32_32x32x16_bf16 v[48:63], v[180:183], v[4:7], v[48:63]
	v_mfma_f32_32x32x16_bf16 v[0:15], v[0:3], v[20:23], 0
	v_mfma_f32_32x32x16_bf16 v[80:95], v[24:27], v[28:31], v[80:95]
	v_mfma_f32_32x32x16_bf16 v[64:79], v[180:183], v[28:31], v[64:79]
	s_waitcnt lgkmcnt(2)
	v_mfma_f32_32x32x16_bf16 v[0:15], v[24:27], v[184:187], v[0:15]
	v_mfma_f32_32x32x16_bf16 v[16:31], v[16:19], v[20:23], 0
	v_mfma_f32_32x32x16_bf16 v[16:31], v[180:183], v[184:187], v[16:31]
	ds_read_b64_tr_b16 v[128:129], v149 offset:55296
	ds_read_b64_tr_b16 v[130:131], v149 offset:57600
	ds_read_b64_tr_b16 v[160:161], v149 offset:57664
	ds_read_b64_tr_b16 v[158:159], v149 offset:55360
	ds_read_b128 v[180:183], v148 offset:64
	ds_read_b128 v[184:187], v148 offset:4672
	s_waitcnt lgkmcnt(1)
	v_mfma_f32_32x32x16_bf16 v[112:127], v[128:131], v[180:183], v[112:127]
	v_mfma_f32_32x32x16_bf16 v[96:111], v[158:161], v[180:183], v[96:111]
	s_waitcnt lgkmcnt(0)
	v_mfma_f32_32x32x16_bf16 v[80:95], v[128:131], v[184:187], v[80:95]
	v_mfma_f32_32x32x16_bf16 v[64:79], v[158:161], v[184:187], v[64:79]
	ds_read_b128 v[180:183], v148 offset:9280
	ds_read_b128 v[184:187], v148 offset:13888
	ds_write_b128 v147, v[132:135] offset:18432
	s_waitcnt vmcnt(1)
	ds_write_b128 v146, v[162:165] offset:55296
	s_waitcnt lgkmcnt(3)
	v_mfma_f32_32x32x16_bf16 v[32:47], v[128:131], v[180:183], v[32:47]
	v_mfma_f32_32x32x16_bf16 v[48:63], v[158:161], v[180:183], v[48:63]
	s_waitcnt lgkmcnt(2)
	v_mfma_f32_32x32x16_bf16 v[0:15], v[128:131], v[184:187], v[0:15]
	v_mfma_f32_32x32x16_bf16 v[16:31], v[158:161], v[184:187], v[16:31]
	ds_read_b64_tr_b16 v[128:129], v149 offset:64512
	ds_read_b64_tr_b16 v[130:131], v150 offset:29952
	ds_read_b64_tr_b16 v[134:135], v150 offset:30016
	ds_read_b64_tr_b16 v[132:133], v149 offset:64576
	ds_read_b128 v[158:161], v148 offset:96
	ds_read_b128 v[162:165], v148 offset:4704
	s_waitcnt lgkmcnt(1)
	v_mfma_f32_32x32x16_bf16 v[112:127], v[128:131], v[158:161], v[112:127]
	v_mfma_f32_32x32x16_bf16 v[96:111], v[132:135], v[158:161], v[96:111]
	s_waitcnt lgkmcnt(0)
	v_mfma_f32_32x32x16_bf16 v[80:95], v[128:131], v[162:165], v[80:95]
	v_mfma_f32_32x32x16_bf16 v[64:79], v[132:135], v[162:165], v[64:79]
	ds_read_b128 v[158:161], v148 offset:9312
	ds_read_b128 v[162:165], v148 offset:13920
	ds_write_b128 v147, v[154:157] offset:27648
	s_waitcnt vmcnt(0)
	ds_write_b128 v146, v[166:169] offset:64512
	v_add3_u32 v156, s1, v153, v170
	v_add_u32_e32 v157, 0x9000, v156
	s_mov_b32 s1, 0x210000
	s_waitcnt lgkmcnt(3)
	v_mfma_f32_32x32x16_bf16 v[32:47], v[128:131], v[158:161], v[32:47]
	s_waitcnt lgkmcnt(2)
	v_mfma_f32_32x32x16_bf16 v[0:15], v[128:131], v[162:165], v[0:15]
	v_add_co_u32_e32 v128, vcc, s35, v144
	s_nop 1
	v_addc_co_u32_e32 v129, vcc, 0, v145, vcc
	v_add_co_u32_e32 v130, vcc, s40, v144
	v_mfma_f32_32x32x16_bf16 v[48:63], v[132:135], v[158:161], v[48:63]
	s_nop 0
	v_addc_co_u32_e32 v131, vcc, 0, v145, vcc
	v_add_co_u32_e32 v154, vcc, s41, v144
	s_nop 1
	v_addc_co_u32_e32 v155, vcc, 0, v145, vcc
	v_add_co_u32_e32 v166, vcc, s42, v144
	v_mfma_f32_32x32x16_bf16 v[16:31], v[132:135], v[162:165], v[16:31]
	s_nop 0
	v_addc_co_u32_e32 v167, vcc, 0, v145, vcc
	global_load_dwordx4 v[132:135], v[128:129], off
	global_load_dwordx4 v[158:161], v[130:131], off
	global_load_dwordx4 v[162:165], v[154:155], off
	s_nop 0
	global_load_dwordx4 v[128:131], v[166:167], off
	s_nop 0
	global_load_dwordx4 v[166:169], v[136:137], off offset:256
	global_load_dwordx4 v[180:183], v[138:139], off offset:256
	global_load_dwordx4 v[184:187], v[140:141], off offset:256
	global_load_dwordx4 v[188:191], v[142:143], off offset:256
	s_waitcnt lgkmcnt(0)
	s_barrier
	ds_read_b64_tr_b16 v[234:235], v156 offset:36864
	ds_read_b64_tr_b16 v[236:237], v156 offset:39168
	ds_read_b128 v[218:221], v172
	ds_read_b64_tr_b16 v[238:239], v156 offset:36928
	ds_read_b64_tr_b16 v[240:241], v156 offset:39232
	ds_read_b128 v[222:225], v172 offset:4608
	ds_read_b128 v[226:229], v172 offset:9216
	ds_read_b128 v[230:233], v172 offset:13824
	s_waitcnt lgkmcnt(5)
	v_mfma_f32_32x32x16_bf16 v[112:127], v[234:237], v[218:221], v[112:127]
	ds_read_b64_tr_b16 v[242:243], v156 offset:46080
	ds_read_b64_tr_b16 v[244:245], v156 offset:48384
	ds_read_b64_tr_b16 v[246:247], v156 offset:46144
	ds_read_b64_tr_b16 v[248:249], v156 offset:48448
	s_waitcnt lgkmcnt(7)
	v_mfma_f32_32x32x16_bf16 v[96:111], v[238:241], v[218:221], v[96:111]
	ds_read_b128 v[218:221], v172 offset:32
	s_waitcnt lgkmcnt(7)
	v_mfma_f32_32x32x16_bf16 v[80:95], v[234:237], v[222:225], v[80:95]
	v_mfma_f32_32x32x16_bf16 v[64:79], v[238:241], v[222:225], v[64:79]
	ds_read_b128 v[222:225], v172 offset:4640
	s_waitcnt vmcnt(3)
	ds_write_b128 v151, v[166:169]
	ds_write_b128 v152, v[132:135] offset:36864
	s_waitcnt lgkmcnt(9)
	v_mfma_f32_32x32x16_bf16 v[32:47], v[234:237], v[226:229], v[32:47]
	v_mfma_f32_32x32x16_bf16 v[48:63], v[238:241], v[226:229], v[48:63]
	ds_read_b128 v[226:229], v172 offset:9248
	s_waitcnt lgkmcnt(9)
	v_mfma_f32_32x32x16_bf16 v[0:15], v[234:237], v[230:233], v[0:15]
	v_mfma_f32_32x32x16_bf16 v[16:31], v[238:241], v[230:233], v[16:31]
	ds_read_b128 v[230:233], v172 offset:13856
	s_waitcnt vmcnt(2)
	ds_write_b128 v151, v[180:183] offset:9216
	ds_write_b128 v152, v[158:161] offset:46080
	s_waitcnt lgkmcnt(7)
	v_mfma_f32_32x32x16_bf16 v[112:127], v[242:245], v[218:221], v[112:127]
	ds_read_b64_tr_b16 v[234:235], v156 offset:55296
	ds_read_b64_tr_b16 v[236:237], v156 offset:57600
	ds_read_b64_tr_b16 v[238:239], v156 offset:55360
	ds_read_b64_tr_b16 v[240:241], v156 offset:57664
	v_mfma_f32_32x32x16_bf16 v[96:111], v[246:249], v[218:221], v[96:111]
	ds_read_b128 v[218:221], v172 offset:64
	s_waitcnt lgkmcnt(11)
; DI f32x16 mfma32(bf16x8 a, bf16x8 b, f32x16 c) { return __builtin_amdgcn_mfma_f32_32x32x16_bf16(a, b, c, 0, 0, 0); }
; DI s16x4 tr_read(const char* p) { bfx4 r = __builtin_amdgcn_ds_read_tr16_b64_v4bf16((LDS_AS bfx4*)p); return __builtin_bit_cast(s16x4, r); }
; DI bf16x8 cat8(s16x4 lo, s16x4 hi) { return __builtin_shufflevector(lo, hi, 0, 1, 2, 3, 4, 5, 6, 7); }
; template <int BM, class Epi>
; DI void gemm_tile(const bf16_t* __restrict__ A, int lda, const bf16_t* __restrict__ B, int ldb, int K, int row0, int col0, const Epi& epi, char* smem) {
;     ...
;     for (int kt = 0; kt < nk; ++kt) {
;         const char* cur = smem + (kt & 1) * GSTAGE;
;         char* nxt = smem + ((kt & 1) ^ 1) * GSTAGE;
;         const bool w1 = kt + 1 < nk, l2 = kt + 2 < nk;
;         const bf16_t* a2 = ag + (size_t)(kt + 2) * 64; const bf16_t* b2 = bg + (size_t)(kt + 2) * 64 * ldb;
; #pragma unroll
;         for (int s = 0; s < 4; ++s) {
;             bf16x8 xf[MI], wf[2];
; #pragma unroll
;             for (int mi = 0; mi < MI; ++mi) xf[mi] = *(const bf16x8*)(cur + xoff + mi * 32 * GA_S + s * 32);
; #pragma unroll
;             for (int ni = 0; ni < 2; ++ni) {
;                 const char* wp = cur + woff + s * 16 * GB_S + ni * 64;
;                 wf[ni] = cat8(tr_read(wp), tr_read(wp + 4 * GB_S));
;             }
; #pragma unroll
;             for (int mi = 0; mi < MI; ++mi)
; #pragma unroll
;                 for (int ni = 0; ni < 2; ++ni) acc[mi][ni] = mfma32(wf[ni], xf[mi], acc[mi][ni]);
;             if (w1) {
;                 if (s < NA_) *(u32x4*)(nxt + aw + 64 * s * GA_S) = ra[s];
;                 *(u32x4*)(nxt + bw + 16 * s * GB_S) = rb[s];
;             }
;             if (l2) {
;                 if (s < NA_) ra[s] = *(const u32x4*)(a2 + (size_t)(64 * s) * lda);
;                 rb[s] = *(const u32x4*)(b2 + (size_t)(16 * s) * ldb);
;             }
;         }
	v_mfma_f32_32x32x16_bf16 v[80:95], v[242:245], v[222:225], v[80:95]
	v_mfma_f32_32x32x16_bf16 v[64:79], v[246:249], v[222:225], v[64:79]
	ds_read_b128 v[222:225], v172 offset:4672
	s_waitcnt vmcnt(1)
	ds_write_b128 v151, v[184:187] offset:18432
	ds_write_b128 v152, v[162:165] offset:55296
	s_waitcnt lgkmcnt(11)
	v_mfma_f32_32x32x16_bf16 v[32:47], v[242:245], v[226:229], v[32:47]
	v_mfma_f32_32x32x16_bf16 v[48:63], v[246:249], v[226:229], v[48:63]
	ds_read_b128 v[226:229], v172 offset:9280
	s_waitcnt lgkmcnt(11)
	v_mfma_f32_32x32x16_bf16 v[0:15], v[242:245], v[230:233], v[0:15]
	v_mfma_f32_32x32x16_bf16 v[16:31], v[246:249], v[230:233], v[16:31]
	ds_read_b128 v[230:233], v172 offset:13888
	s_waitcnt vmcnt(0)
	ds_write_b128 v151, v[188:191] offset:27648
	ds_write_b128 v152, v[128:131] offset:64512
	s_waitcnt lgkmcnt(7)
	v_mfma_f32_32x32x16_bf16 v[112:127], v[234:237], v[218:221], v[112:127]
	ds_read_b64_tr_b16 v[242:243], v156 offset:64512
	ds_read_b64_tr_b16 v[244:245], v157 offset:29952
	ds_read_b64_tr_b16 v[246:247], v156 offset:64576
	ds_read_b64_tr_b16 v[248:249], v157 offset:30016
	v_mfma_f32_32x32x16_bf16 v[96:111], v[238:241], v[218:221], v[96:111]
	ds_read_b128 v[218:221], v172 offset:96
	v_add_co_u32_e32 v128, vcc, s1, v144
	s_mov_b32 s1, 0x2c0000
	s_nop 0
	v_addc_co_u32_e32 v129, vcc, 0, v145, vcc
	s_waitcnt lgkmcnt(11)
	v_mfma_f32_32x32x16_bf16 v[80:95], v[234:237], v[222:225], v[80:95]
	v_mfma_f32_32x32x16_bf16 v[64:79], v[238:241], v[222:225], v[64:79]
	ds_read_b128 v[222:225], v172 offset:4704
	v_add_co_u32_e32 v130, vcc, s60, v144
	s_nop 1
	v_addc_co_u32_e32 v131, vcc, 0, v145, vcc
	v_add_co_u32_e32 v154, vcc, s43, v144
	s_nop 1
	v_addc_co_u32_e32 v155, vcc, 0, v145, vcc
	s_waitcnt lgkmcnt(9)
	v_mfma_f32_32x32x16_bf16 v[32:47], v[234:237], v[226:229], v[32:47]
	v_mfma_f32_32x32x16_bf16 v[48:63], v[238:241], v[226:229], v[48:63]
	ds_read_b128 v[226:229], v172 offset:9312
	v_add_co_u32_e32 v166, vcc, s61, v144
	s_nop 1
	v_addc_co_u32_e32 v167, vcc, 0, v145, vcc
	global_load_dwordx4 v[132:135], v[128:129], off
	s_waitcnt lgkmcnt(9)
	v_mfma_f32_32x32x16_bf16 v[0:15], v[234:237], v[230:233], v[0:15]
	v_mfma_f32_32x32x16_bf16 v[16:31], v[238:241], v[230:233], v[16:31]
	ds_read_b128 v[230:233], v172 offset:13920
	global_load_dwordx4 v[158:161], v[130:131], off
	global_load_dwordx4 v[162:165], v[154:155], off
	s_waitcnt lgkmcnt(3)
	v_mfma_f32_32x32x16_bf16 v[112:127], v[242:245], v[218:221], v[112:127]
	v_mfma_f32_32x32x16_bf16 v[96:111], v[246:249], v[218:221], v[96:111]
	s_nop 0
	global_load_dwordx4 v[128:131], v[166:167], off
	s_nop 0
	global_load_dwordx4 v[166:169], v[136:137], off offset:384
	s_waitcnt lgkmcnt(2)
	v_mfma_f32_32x32x16_bf16 v[80:95], v[242:245], v[222:225], v[80:95]
	v_mfma_f32_32x32x16_bf16 v[64:79], v[246:249], v[222:225], v[64:79]
	global_load_dwordx4 v[180:183], v[138:139], off offset:384
	global_load_dwordx4 v[184:187], v[140:141], off offset:384
	global_load_dwordx4 v[188:191], v[142:143], off offset:384
	s_waitcnt lgkmcnt(0)
	s_barrier
	ds_read_b64_tr_b16 v[234:235], v149 offset:36864
	ds_read_b64_tr_b16 v[236:237], v149 offset:39168
	ds_read_b128 v[218:221], v148
	ds_read_b64_tr_b16 v[238:239], v149 offset:36928
	ds_read_b64_tr_b16 v[240:241], v149 offset:39232
	ds_read_b128 v[222:225], v148 offset:4608
	v_mfma_f32_32x32x16_bf16 v[32:47], v[242:245], v[226:229], v[32:47]
	v_mfma_f32_32x32x16_bf16 v[48:63], v[246:249], v[226:229], v[48:63]
	v_mfma_f32_32x32x16_bf16 v[0:15], v[242:245], v[230:233], v[0:15]
	v_mfma_f32_32x32x16_bf16 v[16:31], v[246:249], v[230:233], v[16:31]
	ds_read_b128 v[226:229], v148 offset:9216
	ds_read_b128 v[230:233], v148 offset:13824
	s_waitcnt lgkmcnt(5)
	v_mfma_f32_32x32x16_bf16 v[112:127], v[234:237], v[218:221], v[112:127]
	ds_read_b64_tr_b16 v[242:243], v149 offset:46080
	ds_read_b64_tr_b16 v[244:245], v149 offset:48384
	ds_read_b64_tr_b16 v[246:247], v149 offset:46144
	ds_read_b64_tr_b16 v[248:249], v149 offset:48448
	s_waitcnt lgkmcnt(7)
	v_mfma_f32_32x32x16_bf16 v[96:111], v[238:241], v[218:221], v[96:111]
	ds_read_b128 v[218:221], v148 offset:32
	s_waitcnt lgkmcnt(7)
	v_mfma_f32_32x32x16_bf16 v[80:95], v[234:237], v[222:225], v[80:95]
	v_mfma_f32_32x32x16_bf16 v[64:79], v[238:241], v[222:225], v[64:79]
	ds_read_b128 v[222:225], v148 offset:4640
	s_waitcnt vmcnt(3)
	ds_write_b128 v147, v[166:169]
	ds_write_b128 v146, v[132:135] offset:36864
	s_waitcnt lgkmcnt(9)
	v_mfma_f32_32x32x16_bf16 v[32:47], v[234:237], v[226:229], v[32:47]
	v_mfma_f32_32x32x16_bf16 v[48:63], v[238:241], v[226:229], v[48:63]
	ds_read_b128 v[226:229], v148 offset:9248
	s_waitcnt lgkmcnt(9)
	v_mfma_f32_32x32x16_bf16 v[0:15], v[234:237], v[230:233], v[0:15]
	v_mfma_f32_32x32x16_bf16 v[16:31], v[238:241], v[230:233], v[16:31]
	ds_read_b128 v[230:233], v148 offset:13856
	s_waitcnt vmcnt(2)
	ds_write_b128 v147, v[180:183] offset:9216
	ds_write_b128 v146, v[158:161] offset:46080
	s_waitcnt lgkmcnt(7)
	v_mfma_f32_32x32x16_bf16 v[112:127], v[242:245], v[218:221], v[112:127]
	ds_read_b64_tr_b16 v[234:235], v149 offset:55296
	ds_read_b64_tr_b16 v[236:237], v149 offset:57600
	ds_read_b64_tr_b16 v[238:239], v149 offset:55360
	ds_read_b64_tr_b16 v[240:241], v149 offset:57664
	v_mfma_f32_32x32x16_bf16 v[96:111], v[246:249], v[218:221], v[96:111]
	ds_read_b128 v[218:221], v148 offset:64
	s_waitcnt lgkmcnt(11)
	v_mfma_f32_32x32x16_bf16 v[80:95], v[242:245], v[222:225], v[80:95]
	v_mfma_f32_32x32x16_bf16 v[64:79], v[246:249], v[222:225], v[64:79]
	ds_read_b128 v[222:225], v148 offset:4672
	s_waitcnt vmcnt(1)
	ds_write_b128 v147, v[184:187] offset:18432
	ds_write_b128 v146, v[162:165] offset:55296
	s_waitcnt lgkmcnt(11)
; DI f32x16 mfma32(bf16x8 a, bf16x8 b, f32x16 c) { return __builtin_amdgcn_mfma_f32_32x32x16_bf16(a, b, c, 0, 0, 0); }
; DI s16x4 tr_read(const char* p) { bfx4 r = __builtin_amdgcn_ds_read_tr16_b64_v4bf16((LDS_AS bfx4*)p); return __builtin_bit_cast(s16x4, r); }
; DI bf16x8 cat8(s16x4 lo, s16x4 hi) { return __builtin_shufflevector(lo, hi, 0, 1, 2, 3, 4, 5, 6, 7); }
; template <int BM, class Epi>
; DI void gemm_tile(const bf16_t* __restrict__ A, int lda, const bf16_t* __restrict__ B, int ldb, int K, int row0, int col0, const Epi& epi, char* smem) {
;     ...
;     for (int kt = 0; kt < nk; ++kt) {
;         const char* cur = smem + (kt & 1) * GSTAGE;
;         char* nxt = smem + ((kt & 1) ^ 1) * GSTAGE;
;         const bool w1 = kt + 1 < nk, l2 = kt + 2 < nk;
;         const bf16_t* a2 = ag + (size_t)(kt + 2) * 64; const bf16_t* b2 = bg + (size_t)(kt + 2) * 64 * ldb;
; #pragma unroll
;         for (int s = 0; s < 4; ++s) {
;             bf16x8 xf[MI], wf[2];
; #pragma unroll
;             for (int mi = 0; mi < MI; ++mi) xf[mi] = *(const bf16x8*)(cur + xoff + mi * 32 * GA_S + s * 32);
; #pragma unroll
;             for (int ni = 0; ni < 2; ++ni) {
;                 const char* wp = cur + woff + s * 16 * GB_S + ni * 64;
;                 wf[ni] = cat8(tr_read(wp), tr_read(wp + 4 * GB_S));
;             }
; #pragma unroll
;             for (int mi = 0; mi < MI; ++mi)
; #pragma unroll
;                 for (int ni = 0; ni < 2; ++ni) acc[mi][ni] = mfma32(wf[ni], xf[mi], acc[mi][ni]);
;             if (w1) {
;                 if (s < NA_) *(u32x4*)(nxt + aw + 64 * s * GA_S) = ra[s];
;                 *(u32x4*)(nxt + bw + 16 * s * GB_S) = rb[s];
;             }
;             if (l2) {
;                 if (s < NA_) ra[s] = *(const u32x4*)(a2 + (size_t)(64 * s) * lda);
;                 rb[s] = *(const u32x4*)(b2 + (size_t)(16 * s) * ldb);
;             }
;         }
	v_mfma_f32_32x32x16_bf16 v[32:47], v[242:245], v[226:229], v[32:47]
	v_mfma_f32_32x32x16_bf16 v[48:63], v[246:249], v[226:229], v[48:63]
	ds_read_b128 v[226:229], v148 offset:9280
	s_waitcnt lgkmcnt(11)
	v_mfma_f32_32x32x16_bf16 v[0:15], v[242:245], v[230:233], v[0:15]
	v_mfma_f32_32x32x16_bf16 v[16:31], v[246:249], v[230:233], v[16:31]
	ds_read_b128 v[230:233], v148 offset:13888
	s_waitcnt vmcnt(0)
	ds_write_b128 v147, v[188:191] offset:27648
	ds_write_b128 v146, v[128:131] offset:64512
	s_waitcnt lgkmcnt(7)
	v_mfma_f32_32x32x16_bf16 v[112:127], v[234:237], v[218:221], v[112:127]
	ds_read_b64_tr_b16 v[242:243], v149 offset:64512
	ds_read_b64_tr_b16 v[244:245], v150 offset:29952
	ds_read_b64_tr_b16 v[246:247], v149 offset:64576
	ds_read_b64_tr_b16 v[248:249], v150 offset:30016
	v_mfma_f32_32x32x16_bf16 v[96:111], v[238:241], v[218:221], v[96:111]
	ds_read_b128 v[218:221], v148 offset:96
	v_add_co_u32_e32 v128, vcc, s1, v144
	s_mov_b32 s1, 0x370000
	s_nop 0
	v_addc_co_u32_e32 v129, vcc, 0, v145, vcc
	s_waitcnt lgkmcnt(11)
	v_mfma_f32_32x32x16_bf16 v[80:95], v[234:237], v[222:225], v[80:95]
	v_mfma_f32_32x32x16_bf16 v[64:79], v[238:241], v[222:225], v[64:79]
	ds_read_b128 v[222:225], v148 offset:4704
	v_add_co_u32_e32 v130, vcc, s62, v144
	s_nop 1
	v_addc_co_u32_e32 v131, vcc, 0, v145, vcc
	v_add_co_u32_e32 v154, vcc, s63, v144
	s_nop 1
	v_addc_co_u32_e32 v155, vcc, 0, v145, vcc
	s_waitcnt lgkmcnt(9)
	v_mfma_f32_32x32x16_bf16 v[32:47], v[234:237], v[226:229], v[32:47]
	v_mfma_f32_32x32x16_bf16 v[48:63], v[238:241], v[226:229], v[48:63]
	ds_read_b128 v[226:229], v148 offset:9312
	v_add_co_u32_e32 v166, vcc, s64, v144
	s_nop 1
	v_addc_co_u32_e32 v167, vcc, 0, v145, vcc
	global_load_dwordx4 v[132:135], v[128:129], off
	s_waitcnt lgkmcnt(9)
	v_mfma_f32_32x32x16_bf16 v[0:15], v[234:237], v[230:233], v[0:15]
	v_mfma_f32_32x32x16_bf16 v[16:31], v[238:241], v[230:233], v[16:31]
	ds_read_b128 v[230:233], v148 offset:13920
	global_load_dwordx4 v[158:161], v[130:131], off
	global_load_dwordx4 v[162:165], v[154:155], off
	s_waitcnt lgkmcnt(3)
	v_mfma_f32_32x32x16_bf16 v[112:127], v[242:245], v[218:221], v[112:127]
	v_mfma_f32_32x32x16_bf16 v[96:111], v[246:249], v[218:221], v[96:111]
	s_nop 0
	global_load_dwordx4 v[128:131], v[166:167], off
	s_nop 0
	global_load_dwordx4 v[166:169], v[136:137], off offset:512
	s_waitcnt lgkmcnt(2)
	v_mfma_f32_32x32x16_bf16 v[80:95], v[242:245], v[222:225], v[80:95]
	v_mfma_f32_32x32x16_bf16 v[64:79], v[246:249], v[222:225], v[64:79]
	global_load_dwordx4 v[180:183], v[138:139], off offset:512
	global_load_dwordx4 v[184:187], v[140:141], off offset:512
	global_load_dwordx4 v[188:191], v[142:143], off offset:512
	s_waitcnt lgkmcnt(0)
	s_barrier
	ds_read_b64_tr_b16 v[234:235], v156 offset:36864
	ds_read_b64_tr_b16 v[236:237], v156 offset:39168
	ds_read_b128 v[218:221], v172
	ds_read_b64_tr_b16 v[238:239], v156 offset:36928
	ds_read_b64_tr_b16 v[240:241], v156 offset:39232
	ds_read_b128 v[222:225], v172 offset:4608
	v_mfma_f32_32x32x16_bf16 v[32:47], v[242:245], v[226:229], v[32:47]
	v_mfma_f32_32x32x16_bf16 v[48:63], v[246:249], v[226:229], v[48:63]
	v_mfma_f32_32x32x16_bf16 v[0:15], v[242:245], v[230:233], v[0:15]
	v_mfma_f32_32x32x16_bf16 v[16:31], v[246:249], v[230:233], v[16:31]
	ds_read_b128 v[226:229], v172 offset:9216
	ds_read_b128 v[230:233], v172 offset:13824
	s_waitcnt lgkmcnt(5)
	v_mfma_f32_32x32x16_bf16 v[112:127], v[234:237], v[218:221], v[112:127]
	ds_read_b64_tr_b16 v[242:243], v156 offset:46080
	ds_read_b64_tr_b16 v[244:245], v156 offset:48384
	ds_read_b64_tr_b16 v[246:247], v156 offset:46144
	ds_read_b64_tr_b16 v[248:249], v156 offset:48448
	s_waitcnt lgkmcnt(7)
	v_mfma_f32_32x32x16_bf16 v[96:111], v[238:241], v[218:221], v[96:111]
	ds_read_b128 v[218:221], v172 offset:32
	s_waitcnt lgkmcnt(7)
	v_mfma_f32_32x32x16_bf16 v[80:95], v[234:237], v[222:225], v[80:95]
	v_mfma_f32_32x32x16_bf16 v[64:79], v[238:241], v[222:225], v[64:79]
	ds_read_b128 v[222:225], v172 offset:4640
	s_waitcnt vmcnt(3)
	ds_write_b128 v151, v[166:169]
	ds_write_b128 v152, v[132:135] offset:36864
	s_waitcnt lgkmcnt(9)
	v_mfma_f32_32x32x16_bf16 v[32:47], v[234:237], v[226:229], v[32:47]
	v_mfma_f32_32x32x16_bf16 v[48:63], v[238:241], v[226:229], v[48:63]
	ds_read_b128 v[226:229], v172 offset:9248
	s_waitcnt lgkmcnt(9)
	v_mfma_f32_32x32x16_bf16 v[0:15], v[234:237], v[230:233], v[0:15]
	v_mfma_f32_32x32x16_bf16 v[16:31], v[238:241], v[230:233], v[16:31]
	ds_read_b128 v[230:233], v172 offset:13856
	s_waitcnt vmcnt(2)
	ds_write_b128 v151, v[180:183] offset:9216
	ds_write_b128 v152, v[158:161] offset:46080
	s_waitcnt lgkmcnt(7)
	v_mfma_f32_32x32x16_bf16 v[112:127], v[242:245], v[218:221], v[112:127]
	ds_read_b64_tr_b16 v[234:235], v156 offset:55296
	ds_read_b64_tr_b16 v[236:237], v156 offset:57600
	ds_read_b64_tr_b16 v[238:239], v156 offset:55360
	ds_read_b64_tr_b16 v[240:241], v156 offset:57664
	v_mfma_f32_32x32x16_bf16 v[96:111], v[246:249], v[218:221], v[96:111]
	ds_read_b128 v[218:221], v172 offset:64
	s_waitcnt lgkmcnt(11)
	v_mfma_f32_32x32x16_bf16 v[80:95], v[242:245], v[222:225], v[80:95]
	v_mfma_f32_32x32x16_bf16 v[64:79], v[246:249], v[222:225], v[64:79]
	ds_read_b128 v[222:225], v172 offset:4672
	s_waitcnt vmcnt(1)
	ds_write_b128 v151, v[184:187] offset:18432
	ds_write_b128 v152, v[162:165] offset:55296
	s_waitcnt lgkmcnt(11)
	v_mfma_f32_32x32x16_bf16 v[32:47], v[242:245], v[226:229], v[32:47]
	v_mfma_f32_32x32x16_bf16 v[48:63], v[246:249], v[226:229], v[48:63]
	ds_read_b128 v[226:229], v172 offset:9280
	s_waitcnt lgkmcnt(11)
	v_mfma_f32_32x32x16_bf16 v[0:15], v[242:245], v[230:233], v[0:15]
	v_mfma_f32_32x32x16_bf16 v[16:31], v[246:249], v[230:233], v[16:31]
	ds_read_b128 v[230:233], v172 offset:13888
	s_waitcnt vmcnt(0)
; DI f32x16 mfma32(bf16x8 a, bf16x8 b, f32x16 c) { return __builtin_amdgcn_mfma_f32_32x32x16_bf16(a, b, c, 0, 0, 0); }
; DI s16x4 tr_read(const char* p) { bfx4 r = __builtin_amdgcn_ds_read_tr16_b64_v4bf16((LDS_AS bfx4*)p); return __builtin_bit_cast(s16x4, r); }
; DI bf16x8 cat8(s16x4 lo, s16x4 hi) { return __builtin_shufflevector(lo, hi, 0, 1, 2, 3, 4, 5, 6, 7); }
; template <int BM, class Epi>
; DI void gemm_tile(const bf16_t* __restrict__ A, int lda, const bf16_t* __restrict__ B, int ldb, int K, int row0, int col0, const Epi& epi, char* smem) {
;     ...
;     for (int kt = 0; kt < nk; ++kt) {
;         const char* cur = smem + (kt & 1) * GSTAGE;
;         char* nxt = smem + ((kt & 1) ^ 1) * GSTAGE;
;         const bool w1 = kt + 1 < nk, l2 = kt + 2 < nk;
;         const bf16_t* a2 = ag + (size_t)(kt + 2) * 64; const bf16_t* b2 = bg + (size_t)(kt + 2) * 64 * ldb;
; #pragma unroll
;         for (int s = 0; s < 4; ++s) {
;             bf16x8 xf[MI], wf[2];
; #pragma unroll
;             for (int mi = 0; mi < MI; ++mi) xf[mi] = *(const bf16x8*)(cur + xoff + mi * 32 * GA_S + s * 32);
; #pragma unroll
;             for (int ni = 0; ni < 2; ++ni) {
;                 const char* wp = cur + woff + s * 16 * GB_S + ni * 64;
;                 wf[ni] = cat8(tr_read(wp), tr_read(wp + 4 * GB_S));
;             }
; #pragma unroll
;             for (int mi = 0; mi < MI; ++mi)
; #pragma unroll
;                 for (int ni = 0; ni < 2; ++ni) acc[mi][ni] = mfma32(wf[ni], xf[mi], acc[mi][ni]);
;             if (w1) {
;                 if (s < NA_) *(u32x4*)(nxt + aw + 64 * s * GA_S) = ra[s];
;                 *(u32x4*)(nxt + bw + 16 * s * GB_S) = rb[s];
;             }
;             if (l2) {
;                 if (s < NA_) ra[s] = *(const u32x4*)(a2 + (size_t)(64 * s) * lda);
;                 rb[s] = *(const u32x4*)(b2 + (size_t)(16 * s) * ldb);
;             }
;         }
	ds_write_b128 v151, v[188:191] offset:27648
	ds_write_b128 v152, v[128:131] offset:64512
	s_waitcnt lgkmcnt(7)
	v_mfma_f32_32x32x16_bf16 v[112:127], v[234:237], v[218:221], v[112:127]
	ds_read_b64_tr_b16 v[242:243], v156 offset:64512
	ds_read_b64_tr_b16 v[244:245], v157 offset:29952
	ds_read_b64_tr_b16 v[246:247], v156 offset:64576
	ds_read_b64_tr_b16 v[248:249], v157 offset:30016
	v_mfma_f32_32x32x16_bf16 v[96:111], v[238:241], v[218:221], v[96:111]
	ds_read_b128 v[218:221], v172 offset:96
	v_add_co_u32_e32 v128, vcc, s1, v144
	s_mov_b32 s1, 0x580000
	s_nop 0
	v_addc_co_u32_e32 v129, vcc, 0, v145, vcc
	s_waitcnt lgkmcnt(11)
	v_mfma_f32_32x32x16_bf16 v[80:95], v[234:237], v[222:225], v[80:95]
	v_mfma_f32_32x32x16_bf16 v[64:79], v[238:241], v[222:225], v[64:79]
	ds_read_b128 v[222:225], v172 offset:4704
	v_add_co_u32_e32 v130, vcc, s65, v144
	s_nop 1
	v_addc_co_u32_e32 v131, vcc, 0, v145, vcc
	v_add_co_u32_e32 v154, vcc, s66, v144
	s_nop 1
	v_addc_co_u32_e32 v155, vcc, 0, v145, vcc
	s_waitcnt lgkmcnt(9)
	v_mfma_f32_32x32x16_bf16 v[32:47], v[234:237], v[226:229], v[32:47]
	v_mfma_f32_32x32x16_bf16 v[48:63], v[238:241], v[226:229], v[48:63]
	ds_read_b128 v[226:229], v172 offset:9312
	v_add_co_u32_e32 v166, vcc, s67, v144
	s_nop 1
	v_addc_co_u32_e32 v167, vcc, 0, v145, vcc
	global_load_dwordx4 v[132:135], v[128:129], off
	s_waitcnt lgkmcnt(9)
	v_mfma_f32_32x32x16_bf16 v[0:15], v[234:237], v[230:233], v[0:15]
	v_mfma_f32_32x32x16_bf16 v[16:31], v[238:241], v[230:233], v[16:31]
	ds_read_b128 v[230:233], v172 offset:13920
	global_load_dwordx4 v[158:161], v[130:131], off
	global_load_dwordx4 v[162:165], v[154:155], off
	s_waitcnt lgkmcnt(3)
	v_mfma_f32_32x32x16_bf16 v[112:127], v[242:245], v[218:221], v[112:127]
	v_mfma_f32_32x32x16_bf16 v[96:111], v[246:249], v[218:221], v[96:111]
	s_nop 0
	global_load_dwordx4 v[128:131], v[166:167], off
	s_nop 0
	global_load_dwordx4 v[166:169], v[136:137], off offset:640
	s_waitcnt lgkmcnt(2)
	v_mfma_f32_32x32x16_bf16 v[80:95], v[242:245], v[222:225], v[80:95]
	v_mfma_f32_32x32x16_bf16 v[64:79], v[246:249], v[222:225], v[64:79]
	global_load_dwordx4 v[180:183], v[138:139], off offset:640
	global_load_dwordx4 v[184:187], v[140:141], off offset:640
	global_load_dwordx4 v[188:191], v[142:143], off offset:640
	s_waitcnt lgkmcnt(0)
	s_barrier
	ds_read_b64_tr_b16 v[234:235], v149 offset:36864
	ds_read_b64_tr_b16 v[236:237], v149 offset:39168
	ds_read_b128 v[218:221], v148
	ds_read_b64_tr_b16 v[238:239], v149 offset:36928
	ds_read_b64_tr_b16 v[240:241], v149 offset:39232
	ds_read_b128 v[222:225], v148 offset:4608
	v_mfma_f32_32x32x16_bf16 v[32:47], v[242:245], v[226:229], v[32:47]
	v_mfma_f32_32x32x16_bf16 v[48:63], v[246:249], v[226:229], v[48:63]
	v_mfma_f32_32x32x16_bf16 v[0:15], v[242:245], v[230:233], v[0:15]
	v_mfma_f32_32x32x16_bf16 v[16:31], v[246:249], v[230:233], v[16:31]
	ds_read_b128 v[226:229], v148 offset:9216
	ds_read_b128 v[230:233], v148 offset:13824
	s_waitcnt lgkmcnt(5)
	v_mfma_f32_32x32x16_bf16 v[112:127], v[234:237], v[218:221], v[112:127]
	ds_read_b64_tr_b16 v[242:243], v149 offset:46080
	ds_read_b64_tr_b16 v[244:245], v149 offset:48384
	ds_read_b64_tr_b16 v[246:247], v149 offset:46144
	ds_read_b64_tr_b16 v[248:249], v149 offset:48448
	s_waitcnt lgkmcnt(7)
	v_mfma_f32_32x32x16_bf16 v[96:111], v[238:241], v[218:221], v[96:111]
	ds_read_b128 v[218:221], v148 offset:32
	s_waitcnt lgkmcnt(7)
	v_mfma_f32_32x32x16_bf16 v[80:95], v[234:237], v[222:225], v[80:95]
	v_mfma_f32_32x32x16_bf16 v[64:79], v[238:241], v[222:225], v[64:79]
	ds_read_b128 v[222:225], v148 offset:4640
	s_waitcnt vmcnt(3)
	ds_write_b128 v147, v[166:169]
	ds_write_b128 v146, v[132:135] offset:36864
	s_waitcnt lgkmcnt(9)
	v_mfma_f32_32x32x16_bf16 v[32:47], v[234:237], v[226:229], v[32:47]
	v_mfma_f32_32x32x16_bf16 v[48:63], v[238:241], v[226:229], v[48:63]
	ds_read_b128 v[226:229], v148 offset:9248
	s_waitcnt lgkmcnt(9)
	v_mfma_f32_32x32x16_bf16 v[0:15], v[234:237], v[230:233], v[0:15]
	v_mfma_f32_32x32x16_bf16 v[16:31], v[238:241], v[230:233], v[16:31]
	ds_read_b128 v[230:233], v148 offset:13856
	s_waitcnt vmcnt(2)
	ds_write_b128 v147, v[180:183] offset:9216
	ds_write_b128 v146, v[158:161] offset:46080
	s_waitcnt lgkmcnt(7)
	v_mfma_f32_32x32x16_bf16 v[112:127], v[242:245], v[218:221], v[112:127]
	ds_read_b64_tr_b16 v[234:235], v149 offset:55296
	ds_read_b64_tr_b16 v[236:237], v149 offset:57600
	ds_read_b64_tr_b16 v[238:239], v149 offset:55360
	ds_read_b64_tr_b16 v[240:241], v149 offset:57664
	v_mfma_f32_32x32x16_bf16 v[96:111], v[246:249], v[218:221], v[96:111]
	ds_read_b128 v[218:221], v148 offset:64
	s_waitcnt lgkmcnt(11)
	v_mfma_f32_32x32x16_bf16 v[80:95], v[242:245], v[222:225], v[80:95]
	v_mfma_f32_32x32x16_bf16 v[64:79], v[246:249], v[222:225], v[64:79]
	ds_read_b128 v[222:225], v148 offset:4672
	s_waitcnt vmcnt(1)
	ds_write_b128 v147, v[184:187] offset:18432
	ds_write_b128 v146, v[162:165] offset:55296
	s_waitcnt lgkmcnt(11)
	v_mfma_f32_32x32x16_bf16 v[32:47], v[242:245], v[226:229], v[32:47]
	v_mfma_f32_32x32x16_bf16 v[48:63], v[246:249], v[226:229], v[48:63]
	ds_read_b128 v[226:229], v148 offset:9280
	s_waitcnt lgkmcnt(11)
	v_mfma_f32_32x32x16_bf16 v[0:15], v[242:245], v[230:233], v[0:15]
	v_mfma_f32_32x32x16_bf16 v[16:31], v[246:249], v[230:233], v[16:31]
	ds_read_b128 v[230:233], v148 offset:13888
	s_waitcnt vmcnt(0)
	ds_write_b128 v147, v[188:191] offset:27648
	ds_write_b128 v146, v[128:131] offset:64512
	s_waitcnt lgkmcnt(7)
; DI f32x16 mfma32(bf16x8 a, bf16x8 b, f32x16 c) { return __builtin_amdgcn_mfma_f32_32x32x16_bf16(a, b, c, 0, 0, 0); }
; DI s16x4 tr_read(const char* p) { bfx4 r = __builtin_amdgcn_ds_read_tr16_b64_v4bf16((LDS_AS bfx4*)p); return __builtin_bit_cast(s16x4, r); }
; DI bf16x8 cat8(s16x4 lo, s16x4 hi) { return __builtin_shufflevector(lo, hi, 0, 1, 2, 3, 4, 5, 6, 7); }
; template <int BM, class Epi>
; DI void gemm_tile(const bf16_t* __restrict__ A, int lda, const bf16_t* __restrict__ B, int ldb, int K, int row0, int col0, const Epi& epi, char* smem) {
;     ...
;     for (int kt = 0; kt < nk; ++kt) {
;         const char* cur = smem + (kt & 1) * GSTAGE;
;         char* nxt = smem + ((kt & 1) ^ 1) * GSTAGE;
;         const bool w1 = kt + 1 < nk, l2 = kt + 2 < nk;
;         const bf16_t* a2 = ag + (size_t)(kt + 2) * 64; const bf16_t* b2 = bg + (size_t)(kt + 2) * 64 * ldb;
; #pragma unroll
;         for (int s = 0; s < 4; ++s) {
;             bf16x8 xf[MI], wf[2];
; #pragma unroll
;             for (int mi = 0; mi < MI; ++mi) xf[mi] = *(const bf16x8*)(cur + xoff + mi * 32 * GA_S + s * 32);
; #pragma unroll
;             for (int ni = 0; ni < 2; ++ni) {
;                 const char* wp = cur + woff + s * 16 * GB_S + ni * 64;
;                 wf[ni] = cat8(tr_read(wp), tr_read(wp + 4 * GB_S));
;             }
; #pragma unroll
;             for (int mi = 0; mi < MI; ++mi)
; #pragma unroll
;                 for (int ni = 0; ni < 2; ++ni) acc[mi][ni] = mfma32(wf[ni], xf[mi], acc[mi][ni]);
;             if (w1) {
;                 if (s < NA_) *(u32x4*)(nxt + aw + 64 * s * GA_S) = ra[s];
;                 *(u32x4*)(nxt + bw + 16 * s * GB_S) = rb[s];
;             }
;             if (l2) {
;                 if (s < NA_) ra[s] = *(const u32x4*)(a2 + (size_t)(64 * s) * lda);
;                 rb[s] = *(const u32x4*)(b2 + (size_t)(16 * s) * ldb);
;             }
;         }
	v_mfma_f32_32x32x16_bf16 v[112:127], v[234:237], v[218:221], v[112:127]
	ds_read_b64_tr_b16 v[242:243], v149 offset:64512
	ds_read_b64_tr_b16 v[244:245], v150 offset:29952
	ds_read_b64_tr_b16 v[246:247], v149 offset:64576
	ds_read_b64_tr_b16 v[248:249], v150 offset:30016
	v_mfma_f32_32x32x16_bf16 v[96:111], v[238:241], v[218:221], v[96:111]
	ds_read_b128 v[218:221], v148 offset:96
	v_add_co_u32_e32 v128, vcc, s68, v144
	s_nop 1
	v_addc_co_u32_e32 v129, vcc, 0, v145, vcc
	v_add_co_u32_e32 v130, vcc, s69, v144
	s_nop 1
	v_addc_co_u32_e32 v131, vcc, 0, v145, vcc
	s_waitcnt lgkmcnt(11)
	v_mfma_f32_32x32x16_bf16 v[80:95], v[234:237], v[222:225], v[80:95]
	v_mfma_f32_32x32x16_bf16 v[64:79], v[238:241], v[222:225], v[64:79]
	ds_read_b128 v[222:225], v148 offset:4704
	v_add_co_u32_e32 v154, vcc, s70, v144
	s_nop 1
	v_addc_co_u32_e32 v155, vcc, 0, v145, vcc
	v_add_co_u32_e32 v166, vcc, s71, v144
	s_nop 1
	v_addc_co_u32_e32 v167, vcc, 0, v145, vcc
	s_waitcnt lgkmcnt(9)
	v_mfma_f32_32x32x16_bf16 v[32:47], v[234:237], v[226:229], v[32:47]
	v_mfma_f32_32x32x16_bf16 v[48:63], v[238:241], v[226:229], v[48:63]
	ds_read_b128 v[226:229], v148 offset:9312
	global_load_dwordx4 v[132:135], v[128:129], off
	global_load_dwordx4 v[158:161], v[130:131], off
	s_waitcnt lgkmcnt(9)
	v_mfma_f32_32x32x16_bf16 v[0:15], v[234:237], v[230:233], v[0:15]
	v_mfma_f32_32x32x16_bf16 v[16:31], v[238:241], v[230:233], v[16:31]
	ds_read_b128 v[230:233], v148 offset:13920
	global_load_dwordx4 v[162:165], v[154:155], off
	s_nop 0
	global_load_dwordx4 v[128:131], v[166:167], off
	s_waitcnt lgkmcnt(3)
	v_mfma_f32_32x32x16_bf16 v[112:127], v[242:245], v[218:221], v[112:127]
	v_mfma_f32_32x32x16_bf16 v[96:111], v[246:249], v[218:221], v[96:111]
	s_nop 0
	global_load_dwordx4 v[166:169], v[136:137], off offset:768
	global_load_dwordx4 v[180:183], v[138:139], off offset:768
	s_waitcnt lgkmcnt(2)
	v_mfma_f32_32x32x16_bf16 v[80:95], v[242:245], v[222:225], v[80:95]
	v_mfma_f32_32x32x16_bf16 v[64:79], v[246:249], v[222:225], v[64:79]
	global_load_dwordx4 v[184:187], v[140:141], off offset:768
	global_load_dwordx4 v[188:191], v[142:143], off offset:768
	s_waitcnt lgkmcnt(0)
	s_barrier
	ds_read_b64_tr_b16 v[234:235], v156 offset:36864
	ds_read_b64_tr_b16 v[236:237], v156 offset:39168
	ds_read_b128 v[218:221], v172
	ds_read_b64_tr_b16 v[238:239], v156 offset:36928
	ds_read_b64_tr_b16 v[240:241], v156 offset:39232
	ds_read_b128 v[222:225], v172 offset:4608
	v_mfma_f32_32x32x16_bf16 v[32:47], v[242:245], v[226:229], v[32:47]
	v_mfma_f32_32x32x16_bf16 v[48:63], v[246:249], v[226:229], v[48:63]
	v_mfma_f32_32x32x16_bf16 v[0:15], v[242:245], v[230:233], v[0:15]
	v_mfma_f32_32x32x16_bf16 v[16:31], v[246:249], v[230:233], v[16:31]
	ds_read_b128 v[226:229], v172 offset:9216
	ds_read_b128 v[230:233], v172 offset:13824
	s_waitcnt lgkmcnt(5)
	v_mfma_f32_32x32x16_bf16 v[112:127], v[234:237], v[218:221], v[112:127]
	ds_read_b64_tr_b16 v[242:243], v156 offset:46080
	ds_read_b64_tr_b16 v[244:245], v156 offset:48384
	ds_read_b64_tr_b16 v[246:247], v156 offset:46144
	ds_read_b64_tr_b16 v[248:249], v156 offset:48448
	s_waitcnt lgkmcnt(7)
	v_mfma_f32_32x32x16_bf16 v[96:111], v[238:241], v[218:221], v[96:111]
	ds_read_b128 v[218:221], v172 offset:32
	s_waitcnt lgkmcnt(7)
	v_mfma_f32_32x32x16_bf16 v[80:95], v[234:237], v[222:225], v[80:95]
	v_mfma_f32_32x32x16_bf16 v[64:79], v[238:241], v[222:225], v[64:79]
	ds_read_b128 v[222:225], v172 offset:4640
	s_waitcnt vmcnt(3)
	ds_write_b128 v151, v[166:169]
	ds_write_b128 v152, v[132:135] offset:36864
	s_waitcnt lgkmcnt(9)
	v_mfma_f32_32x32x16_bf16 v[32:47], v[234:237], v[226:229], v[32:47]
	v_mfma_f32_32x32x16_bf16 v[48:63], v[238:241], v[226:229], v[48:63]
	ds_read_b128 v[226:229], v172 offset:9248
	s_waitcnt lgkmcnt(9)
	v_mfma_f32_32x32x16_bf16 v[0:15], v[234:237], v[230:233], v[0:15]
	v_mfma_f32_32x32x16_bf16 v[16:31], v[238:241], v[230:233], v[16:31]
	ds_read_b128 v[230:233], v172 offset:13856
	s_waitcnt vmcnt(2)
	ds_write_b128 v151, v[180:183] offset:9216
	ds_write_b128 v152, v[158:161] offset:46080
	s_waitcnt lgkmcnt(7)
	v_mfma_f32_32x32x16_bf16 v[112:127], v[242:245], v[218:221], v[112:127]
	ds_read_b64_tr_b16 v[234:235], v156 offset:55296
	ds_read_b64_tr_b16 v[236:237], v156 offset:57600
	ds_read_b64_tr_b16 v[238:239], v156 offset:55360
	ds_read_b64_tr_b16 v[240:241], v156 offset:57664
	v_mfma_f32_32x32x16_bf16 v[96:111], v[246:249], v[218:221], v[96:111]
	ds_read_b128 v[218:221], v172 offset:64
	s_waitcnt lgkmcnt(11)
	v_mfma_f32_32x32x16_bf16 v[80:95], v[242:245], v[222:225], v[80:95]
	v_mfma_f32_32x32x16_bf16 v[64:79], v[246:249], v[222:225], v[64:79]
	ds_read_b128 v[222:225], v172 offset:4672
	s_waitcnt vmcnt(1)
	ds_write_b128 v151, v[184:187] offset:18432
	ds_write_b128 v152, v[162:165] offset:55296
	s_waitcnt lgkmcnt(11)
	v_mfma_f32_32x32x16_bf16 v[32:47], v[242:245], v[226:229], v[32:47]
	v_mfma_f32_32x32x16_bf16 v[48:63], v[246:249], v[226:229], v[48:63]
	ds_read_b128 v[226:229], v172 offset:9280
	s_waitcnt lgkmcnt(11)
	v_mfma_f32_32x32x16_bf16 v[0:15], v[242:245], v[230:233], v[0:15]
	v_mfma_f32_32x32x16_bf16 v[16:31], v[246:249], v[230:233], v[16:31]
	ds_read_b128 v[230:233], v172 offset:13888
	s_waitcnt vmcnt(0)
	ds_write_b128 v151, v[188:191] offset:27648
	ds_write_b128 v152, v[128:131] offset:64512
	s_waitcnt lgkmcnt(7)
	v_mfma_f32_32x32x16_bf16 v[112:127], v[234:237], v[218:221], v[112:127]
	ds_read_b64_tr_b16 v[242:243], v156 offset:64512
	ds_read_b64_tr_b16 v[244:245], v157 offset:29952
	ds_read_b64_tr_b16 v[246:247], v156 offset:64576
	ds_read_b64_tr_b16 v[248:249], v157 offset:30016
	v_mfma_f32_32x32x16_bf16 v[96:111], v[238:241], v[218:221], v[96:111]
	ds_read_b128 v[218:221], v172 offset:96
	v_add_co_u32_e32 v128, vcc, s72, v144
	s_nop 1
	v_addc_co_u32_e32 v129, vcc, 0, v145, vcc
	v_add_co_u32_e32 v130, vcc, s73, v144
	s_nop 1
	v_addc_co_u32_e32 v131, vcc, 0, v145, vcc
	s_waitcnt lgkmcnt(11)
; DI f32x16 mfma32(bf16x8 a, bf16x8 b, f32x16 c) { return __builtin_amdgcn_mfma_f32_32x32x16_bf16(a, b, c, 0, 0, 0); }
; DI s16x4 tr_read(const char* p) { bfx4 r = __builtin_amdgcn_ds_read_tr16_b64_v4bf16((LDS_AS bfx4*)p); return __builtin_bit_cast(s16x4, r); }
; DI bf16x8 cat8(s16x4 lo, s16x4 hi) { return __builtin_shufflevector(lo, hi, 0, 1, 2, 3, 4, 5, 6, 7); }
; template <int BM, class Epi>
; DI void gemm_tile(const bf16_t* __restrict__ A, int lda, const bf16_t* __restrict__ B, int ldb, int K, int row0, int col0, const Epi& epi, char* smem) {
;     ...
;     for (int kt = 0; kt < nk; ++kt) {
;         const char* cur = smem + (kt & 1) * GSTAGE;
;         char* nxt = smem + ((kt & 1) ^ 1) * GSTAGE;
;         const bool w1 = kt + 1 < nk, l2 = kt + 2 < nk;
;         const bf16_t* a2 = ag + (size_t)(kt + 2) * 64; const bf16_t* b2 = bg + (size_t)(kt + 2) * 64 * ldb;
; #pragma unroll
;         for (int s = 0; s < 4; ++s) {
;             bf16x8 xf[MI], wf[2];
; #pragma unroll
;             for (int mi = 0; mi < MI; ++mi) xf[mi] = *(const bf16x8*)(cur + xoff + mi * 32 * GA_S + s * 32);
; #pragma unroll
;             for (int ni = 0; ni < 2; ++ni) {
;                 const char* wp = cur + woff + s * 16 * GB_S + ni * 64;
;                 wf[ni] = cat8(tr_read(wp), tr_read(wp + 4 * GB_S));
;             }
; #pragma unroll
;             for (int mi = 0; mi < MI; ++mi)
; #pragma unroll
;                 for (int ni = 0; ni < 2; ++ni) acc[mi][ni] = mfma32(wf[ni], xf[mi], acc[mi][ni]);
;             if (w1) {
;                 if (s < NA_) *(u32x4*)(nxt + aw + 64 * s * GA_S) = ra[s];
;                 *(u32x4*)(nxt + bw + 16 * s * GB_S) = rb[s];
;             }
;             if (l2) {
;                 if (s < NA_) ra[s] = *(const u32x4*)(a2 + (size_t)(64 * s) * lda);
;                 rb[s] = *(const u32x4*)(b2 + (size_t)(16 * s) * ldb);
;             }
;         }
	v_mfma_f32_32x32x16_bf16 v[80:95], v[234:237], v[222:225], v[80:95]
	v_mfma_f32_32x32x16_bf16 v[64:79], v[238:241], v[222:225], v[64:79]
	ds_read_b128 v[222:225], v172 offset:4704
	v_add_co_u32_e32 v154, vcc, s74, v144
	s_nop 1
	v_addc_co_u32_e32 v155, vcc, 0, v145, vcc
	v_add_co_u32_e32 v166, vcc, s75, v144
	s_nop 1
	v_addc_co_u32_e32 v167, vcc, 0, v145, vcc
	s_waitcnt lgkmcnt(9)
	v_mfma_f32_32x32x16_bf16 v[32:47], v[234:237], v[226:229], v[32:47]
	v_mfma_f32_32x32x16_bf16 v[48:63], v[238:241], v[226:229], v[48:63]
	ds_read_b128 v[226:229], v172 offset:9312
	global_load_dwordx4 v[132:135], v[128:129], off
	global_load_dwordx4 v[158:161], v[130:131], off
	s_waitcnt lgkmcnt(9)
	v_mfma_f32_32x32x16_bf16 v[0:15], v[234:237], v[230:233], v[0:15]
	v_mfma_f32_32x32x16_bf16 v[16:31], v[238:241], v[230:233], v[16:31]
	ds_read_b128 v[230:233], v172 offset:13920
	global_load_dwordx4 v[162:165], v[154:155], off
	s_nop 0
	global_load_dwordx4 v[128:131], v[166:167], off
	s_waitcnt lgkmcnt(3)
	v_mfma_f32_32x32x16_bf16 v[112:127], v[242:245], v[218:221], v[112:127]
	v_mfma_f32_32x32x16_bf16 v[96:111], v[246:249], v[218:221], v[96:111]
	s_nop 0
	global_load_dwordx4 v[166:169], v[136:137], off offset:896
	global_load_dwordx4 v[180:183], v[138:139], off offset:896
	s_waitcnt lgkmcnt(2)
	v_mfma_f32_32x32x16_bf16 v[80:95], v[242:245], v[222:225], v[80:95]
	v_mfma_f32_32x32x16_bf16 v[64:79], v[246:249], v[222:225], v[64:79]
	global_load_dwordx4 v[184:187], v[140:141], off offset:896
	global_load_dwordx4 v[188:191], v[142:143], off offset:896
	s_waitcnt lgkmcnt(0)
	s_barrier
	ds_read_b64_tr_b16 v[234:235], v149 offset:36864
	ds_read_b64_tr_b16 v[236:237], v149 offset:39168
	ds_read_b128 v[218:221], v148
	ds_read_b64_tr_b16 v[238:239], v149 offset:36928
	ds_read_b64_tr_b16 v[240:241], v149 offset:39232
	ds_read_b128 v[222:225], v148 offset:4608
	v_mfma_f32_32x32x16_bf16 v[32:47], v[242:245], v[226:229], v[32:47]
	v_mfma_f32_32x32x16_bf16 v[48:63], v[246:249], v[226:229], v[48:63]
	v_mfma_f32_32x32x16_bf16 v[0:15], v[242:245], v[230:233], v[0:15]
	v_mfma_f32_32x32x16_bf16 v[16:31], v[246:249], v[230:233], v[16:31]
	ds_read_b128 v[226:229], v148 offset:9216
	ds_read_b128 v[230:233], v148 offset:13824
	s_waitcnt lgkmcnt(5)
	v_mfma_f32_32x32x16_bf16 v[112:127], v[234:237], v[218:221], v[112:127]
	ds_read_b64_tr_b16 v[242:243], v149 offset:46080
	ds_read_b64_tr_b16 v[244:245], v149 offset:48384
	ds_read_b64_tr_b16 v[246:247], v149 offset:46144
	ds_read_b64_tr_b16 v[248:249], v149 offset:48448
	s_waitcnt lgkmcnt(7)
	v_mfma_f32_32x32x16_bf16 v[96:111], v[238:241], v[218:221], v[96:111]
	ds_read_b128 v[218:221], v148 offset:32
	s_waitcnt lgkmcnt(7)
	v_mfma_f32_32x32x16_bf16 v[80:95], v[234:237], v[222:225], v[80:95]
	v_mfma_f32_32x32x16_bf16 v[64:79], v[238:241], v[222:225], v[64:79]
	ds_read_b128 v[222:225], v148 offset:4640
	s_waitcnt vmcnt(3)
	ds_write_b128 v147, v[166:169]
	ds_write_b128 v146, v[132:135] offset:36864
	s_waitcnt lgkmcnt(9)
	v_mfma_f32_32x32x16_bf16 v[32:47], v[234:237], v[226:229], v[32:47]
	v_mfma_f32_32x32x16_bf16 v[48:63], v[238:241], v[226:229], v[48:63]
	ds_read_b128 v[226:229], v148 offset:9248
	s_waitcnt lgkmcnt(9)
	v_mfma_f32_32x32x16_bf16 v[0:15], v[234:237], v[230:233], v[0:15]
	v_mfma_f32_32x32x16_bf16 v[16:31], v[238:241], v[230:233], v[16:31]
	ds_read_b128 v[230:233], v148 offset:13856
	s_waitcnt vmcnt(2)
	ds_write_b128 v147, v[180:183] offset:9216
	ds_write_b128 v146, v[158:161] offset:46080
	s_waitcnt lgkmcnt(7)
	v_mfma_f32_32x32x16_bf16 v[112:127], v[242:245], v[218:221], v[112:127]
	ds_read_b64_tr_b16 v[234:235], v149 offset:55296
	ds_read_b64_tr_b16 v[236:237], v149 offset:57600
	ds_read_b64_tr_b16 v[238:239], v149 offset:55360
	ds_read_b64_tr_b16 v[240:241], v149 offset:57664
	v_mfma_f32_32x32x16_bf16 v[96:111], v[246:249], v[218:221], v[96:111]
	ds_read_b128 v[218:221], v148 offset:64
	s_waitcnt lgkmcnt(11)
	v_mfma_f32_32x32x16_bf16 v[80:95], v[242:245], v[222:225], v[80:95]
	v_mfma_f32_32x32x16_bf16 v[64:79], v[246:249], v[222:225], v[64:79]
	ds_read_b128 v[222:225], v148 offset:4672
	s_waitcnt vmcnt(1)
	ds_write_b128 v147, v[184:187] offset:18432
	ds_write_b128 v146, v[162:165] offset:55296
	s_waitcnt lgkmcnt(11)
	v_mfma_f32_32x32x16_bf16 v[32:47], v[242:245], v[226:229], v[32:47]
	v_mfma_f32_32x32x16_bf16 v[48:63], v[246:249], v[226:229], v[48:63]
	ds_read_b128 v[226:229], v148 offset:9280
	s_waitcnt lgkmcnt(11)
	v_mfma_f32_32x32x16_bf16 v[0:15], v[242:245], v[230:233], v[0:15]
	v_mfma_f32_32x32x16_bf16 v[16:31], v[246:249], v[230:233], v[16:31]
	ds_read_b128 v[230:233], v148 offset:13888
	s_waitcnt vmcnt(0)
	ds_write_b128 v147, v[188:191] offset:27648
	ds_write_b128 v146, v[128:131] offset:64512
	s_waitcnt lgkmcnt(7)
	v_mfma_f32_32x32x16_bf16 v[112:127], v[234:237], v[218:221], v[112:127]
	ds_read_b64_tr_b16 v[242:243], v149 offset:64512
	ds_read_b64_tr_b16 v[244:245], v150 offset:29952
	ds_read_b64_tr_b16 v[246:247], v149 offset:64576
	ds_read_b64_tr_b16 v[248:249], v150 offset:30016
	v_mfma_f32_32x32x16_bf16 v[96:111], v[238:241], v[218:221], v[96:111]
	ds_read_b128 v[218:221], v148 offset:96
	v_add_co_u32_e32 v128, vcc, s1, v144
	s_mov_b32 s1, 0x630000
	s_nop 0
	v_addc_co_u32_e32 v129, vcc, 0, v145, vcc
	s_waitcnt lgkmcnt(11)
	v_mfma_f32_32x32x16_bf16 v[80:95], v[234:237], v[222:225], v[80:95]
	v_mfma_f32_32x32x16_bf16 v[64:79], v[238:241], v[222:225], v[64:79]
	ds_read_b128 v[222:225], v148 offset:4704
	v_add_co_u32_e32 v130, vcc, s84, v144
	s_nop 1
	v_addc_co_u32_e32 v131, vcc, 0, v145, vcc
	v_add_co_u32_e32 v154, vcc, s86, v144
	s_nop 1
	v_addc_co_u32_e32 v155, vcc, 0, v145, vcc
	s_waitcnt lgkmcnt(9)
	v_mfma_f32_32x32x16_bf16 v[32:47], v[234:237], v[226:229], v[32:47]
	v_mfma_f32_32x32x16_bf16 v[48:63], v[238:241], v[226:229], v[48:63]
	ds_read_b128 v[226:229], v148 offset:9312
	v_add_co_u32_e32 v166, vcc, s85, v144
	s_nop 1
	v_addc_co_u32_e32 v167, vcc, 0, v145, vcc
	global_load_dwordx4 v[132:135], v[128:129], off
	s_waitcnt lgkmcnt(9)
	v_mfma_f32_32x32x16_bf16 v[0:15], v[234:237], v[230:233], v[0:15]
	v_mfma_f32_32x32x16_bf16 v[16:31], v[238:241], v[230:233], v[16:31]
	ds_read_b128 v[230:233], v148 offset:13920
	global_load_dwordx4 v[158:161], v[130:131], off
	global_load_dwordx4 v[162:165], v[154:155], off
	s_waitcnt lgkmcnt(3)
	v_mfma_f32_32x32x16_bf16 v[112:127], v[242:245], v[218:221], v[112:127]
	v_mfma_f32_32x32x16_bf16 v[96:111], v[246:249], v[218:221], v[96:111]
	s_nop 0
	global_load_dwordx4 v[128:131], v[166:167], off
	s_nop 0
	global_load_dwordx4 v[166:169], v[136:137], off offset:1024
	s_waitcnt lgkmcnt(2)
	v_mfma_f32_32x32x16_bf16 v[80:95], v[242:245], v[222:225], v[80:95]
	v_mfma_f32_32x32x16_bf16 v[64:79], v[246:249], v[222:225], v[64:79]
	global_load_dwordx4 v[180:183], v[138:139], off offset:1024
	global_load_dwordx4 v[184:187], v[140:141], off offset:1024
	global_load_dwordx4 v[188:191], v[142:143], off offset:1024
	s_waitcnt lgkmcnt(0)
	s_barrier
; DI f32x16 mfma32(bf16x8 a, bf16x8 b, f32x16 c) { return __builtin_amdgcn_mfma_f32_32x32x16_bf16(a, b, c, 0, 0, 0); }
; DI s16x4 tr_read(const char* p) { bfx4 r = __builtin_amdgcn_ds_read_tr16_b64_v4bf16((LDS_AS bfx4*)p); return __builtin_bit_cast(s16x4, r); }
; DI bf16x8 cat8(s16x4 lo, s16x4 hi) { return __builtin_shufflevector(lo, hi, 0, 1, 2, 3, 4, 5, 6, 7); }
; template <int BM, class Epi>
; DI void gemm_tile(const bf16_t* __restrict__ A, int lda, const bf16_t* __restrict__ B, int ldb, int K, int row0, int col0, const Epi& epi, char* smem) {
;     ...
;     for (int kt = 0; kt < nk; ++kt) {
;         const char* cur = smem + (kt & 1) * GSTAGE;
;         char* nxt = smem + ((kt & 1) ^ 1) * GSTAGE;
;         const bool w1 = kt + 1 < nk, l2 = kt + 2 < nk;
;         const bf16_t* a2 = ag + (size_t)(kt + 2) * 64; const bf16_t* b2 = bg + (size_t)(kt + 2) * 64 * ldb;
; #pragma unroll
;         for (int s = 0; s < 4; ++s) {
;             bf16x8 xf[MI], wf[2];
; #pragma unroll
;             for (int mi = 0; mi < MI; ++mi) xf[mi] = *(const bf16x8*)(cur + xoff + mi * 32 * GA_S + s * 32);
; #pragma unroll
;             for (int ni = 0; ni < 2; ++ni) {
;                 const char* wp = cur + woff + s * 16 * GB_S + ni * 64;
;                 wf[ni] = cat8(tr_read(wp), tr_read(wp + 4 * GB_S));
;             }
; #pragma unroll
;             for (int mi = 0; mi < MI; ++mi)
; #pragma unroll
;                 for (int ni = 0; ni < 2; ++ni) acc[mi][ni] = mfma32(wf[ni], xf[mi], acc[mi][ni]);
;             if (w1) {
;                 if (s < NA_) *(u32x4*)(nxt + aw + 64 * s * GA_S) = ra[s];
;                 *(u32x4*)(nxt + bw + 16 * s * GB_S) = rb[s];
;             }
;             if (l2) {
;                 if (s < NA_) ra[s] = *(const u32x4*)(a2 + (size_t)(64 * s) * lda);
;                 rb[s] = *(const u32x4*)(b2 + (size_t)(16 * s) * ldb);
;             }
;         }
	ds_read_b64_tr_b16 v[234:235], v156 offset:36864
	ds_read_b64_tr_b16 v[236:237], v156 offset:39168
	ds_read_b128 v[218:221], v172
	ds_read_b64_tr_b16 v[238:239], v156 offset:36928
	ds_read_b64_tr_b16 v[240:241], v156 offset:39232
	ds_read_b128 v[222:225], v172 offset:4608
	v_mfma_f32_32x32x16_bf16 v[32:47], v[242:245], v[226:229], v[32:47]
	v_mfma_f32_32x32x16_bf16 v[48:63], v[246:249], v[226:229], v[48:63]
	v_mfma_f32_32x32x16_bf16 v[0:15], v[242:245], v[230:233], v[0:15]
	v_mfma_f32_32x32x16_bf16 v[16:31], v[246:249], v[230:233], v[16:31]
	ds_read_b128 v[226:229], v172 offset:9216
	ds_read_b128 v[230:233], v172 offset:13824
	s_waitcnt lgkmcnt(5)
	v_mfma_f32_32x32x16_bf16 v[112:127], v[234:237], v[218:221], v[112:127]
	ds_read_b64_tr_b16 v[242:243], v156 offset:46080
	ds_read_b64_tr_b16 v[244:245], v156 offset:48384
	ds_read_b64_tr_b16 v[246:247], v156 offset:46144
	ds_read_b64_tr_b16 v[248:249], v156 offset:48448
	s_waitcnt lgkmcnt(7)
	v_mfma_f32_32x32x16_bf16 v[96:111], v[238:241], v[218:221], v[96:111]
	ds_read_b128 v[218:221], v172 offset:32
	s_waitcnt lgkmcnt(7)
	v_mfma_f32_32x32x16_bf16 v[80:95], v[234:237], v[222:225], v[80:95]
	v_mfma_f32_32x32x16_bf16 v[64:79], v[238:241], v[222:225], v[64:79]
	ds_read_b128 v[222:225], v172 offset:4640
	s_waitcnt vmcnt(3)
	ds_write_b128 v151, v[166:169]
	ds_write_b128 v152, v[132:135] offset:36864
	s_waitcnt lgkmcnt(9)
	v_mfma_f32_32x32x16_bf16 v[32:47], v[234:237], v[226:229], v[32:47]
	v_mfma_f32_32x32x16_bf16 v[48:63], v[238:241], v[226:229], v[48:63]
	ds_read_b128 v[226:229], v172 offset:9248
	s_waitcnt lgkmcnt(9)
	v_mfma_f32_32x32x16_bf16 v[0:15], v[234:237], v[230:233], v[0:15]
	v_mfma_f32_32x32x16_bf16 v[16:31], v[238:241], v[230:233], v[16:31]
	ds_read_b128 v[230:233], v172 offset:13856
	s_waitcnt vmcnt(2)
	ds_write_b128 v151, v[180:183] offset:9216
	ds_write_b128 v152, v[158:161] offset:46080
	s_waitcnt lgkmcnt(7)
	v_mfma_f32_32x32x16_bf16 v[112:127], v[242:245], v[218:221], v[112:127]
	ds_read_b64_tr_b16 v[234:235], v156 offset:55296
	ds_read_b64_tr_b16 v[236:237], v156 offset:57600
	ds_read_b64_tr_b16 v[238:239], v156 offset:55360
	ds_read_b64_tr_b16 v[240:241], v156 offset:57664
	v_mfma_f32_32x32x16_bf16 v[96:111], v[246:249], v[218:221], v[96:111]
	ds_read_b128 v[218:221], v172 offset:64
	s_waitcnt lgkmcnt(11)
	v_mfma_f32_32x32x16_bf16 v[80:95], v[242:245], v[222:225], v[80:95]
	v_mfma_f32_32x32x16_bf16 v[64:79], v[246:249], v[222:225], v[64:79]
	ds_read_b128 v[222:225], v172 offset:4672
	s_waitcnt vmcnt(1)
	ds_write_b128 v151, v[184:187] offset:18432
	ds_write_b128 v152, v[162:165] offset:55296
	s_waitcnt lgkmcnt(11)
	v_mfma_f32_32x32x16_bf16 v[32:47], v[242:245], v[226:229], v[32:47]
	v_mfma_f32_32x32x16_bf16 v[48:63], v[246:249], v[226:229], v[48:63]
	ds_read_b128 v[226:229], v172 offset:9280
	s_waitcnt lgkmcnt(11)
	v_mfma_f32_32x32x16_bf16 v[0:15], v[242:245], v[230:233], v[0:15]
	v_mfma_f32_32x32x16_bf16 v[16:31], v[246:249], v[230:233], v[16:31]
	ds_read_b128 v[230:233], v172 offset:13888
	s_waitcnt vmcnt(0)
	ds_write_b128 v151, v[188:191] offset:27648
	ds_write_b128 v152, v[128:131] offset:64512
	s_waitcnt lgkmcnt(7)
	v_mfma_f32_32x32x16_bf16 v[112:127], v[234:237], v[218:221], v[112:127]
	ds_read_b64_tr_b16 v[242:243], v156 offset:64512
	ds_read_b64_tr_b16 v[244:245], v157 offset:29952
	ds_read_b64_tr_b16 v[246:247], v156 offset:64576
	ds_read_b64_tr_b16 v[248:249], v157 offset:30016
	v_mfma_f32_32x32x16_bf16 v[96:111], v[238:241], v[218:221], v[96:111]
	ds_read_b128 v[218:221], v172 offset:96
	v_add_co_u32_e32 v128, vcc, s1, v144
	s_mov_b32 s1, 0x65c000
	s_nop 0
	v_addc_co_u32_e32 v129, vcc, 0, v145, vcc
	s_waitcnt lgkmcnt(11)
	v_mfma_f32_32x32x16_bf16 v[80:95], v[234:237], v[222:225], v[80:95]
	v_mfma_f32_32x32x16_bf16 v[64:79], v[238:241], v[222:225], v[64:79]
	ds_read_b128 v[222:225], v172 offset:4704
	v_add_co_u32_e32 v130, vcc, s1, v144
	s_mov_b32 s1, 0x688000
	s_nop 0
	v_addc_co_u32_e32 v131, vcc, 0, v145, vcc
	s_waitcnt lgkmcnt(9)
	v_mfma_f32_32x32x16_bf16 v[32:47], v[234:237], v[226:229], v[32:47]
	v_mfma_f32_32x32x16_bf16 v[48:63], v[238:241], v[226:229], v[48:63]
	ds_read_b128 v[226:229], v172 offset:9312
	v_add_co_u32_e32 v154, vcc, s1, v144
	s_mov_b32 s1, 0x6b4000
	s_nop 0
	v_addc_co_u32_e32 v155, vcc, 0, v145, vcc
	s_waitcnt lgkmcnt(9)
	v_mfma_f32_32x32x16_bf16 v[0:15], v[234:237], v[230:233], v[0:15]
	v_mfma_f32_32x32x16_bf16 v[16:31], v[238:241], v[230:233], v[16:31]
	ds_read_b128 v[230:233], v172 offset:13920
	v_add_co_u32_e32 v166, vcc, s1, v144
	s_mov_b32 s1, 0x6e0000
	s_nop 0
	v_addc_co_u32_e32 v167, vcc, 0, v145, vcc
	s_waitcnt lgkmcnt(3)
	v_mfma_f32_32x32x16_bf16 v[112:127], v[242:245], v[218:221], v[112:127]
	v_mfma_f32_32x32x16_bf16 v[96:111], v[246:249], v[218:221], v[96:111]
	global_load_dwordx4 v[132:135], v[128:129], off
	global_load_dwordx4 v[158:161], v[130:131], off
	s_waitcnt lgkmcnt(2)
	v_mfma_f32_32x32x16_bf16 v[80:95], v[242:245], v[222:225], v[80:95]
	v_mfma_f32_32x32x16_bf16 v[64:79], v[246:249], v[222:225], v[64:79]
	global_load_dwordx4 v[162:165], v[154:155], off
	s_nop 0
	global_load_dwordx4 v[128:131], v[166:167], off
	s_nop 0
	global_load_dwordx4 v[166:169], v[136:137], off offset:1152
	global_load_dwordx4 v[180:183], v[138:139], off offset:1152
	global_load_dwordx4 v[184:187], v[140:141], off offset:1152
	global_load_dwordx4 v[188:191], v[142:143], off offset:1152
	s_waitcnt lgkmcnt(0)
	s_barrier
; DI f32x16 mfma32(bf16x8 a, bf16x8 b, f32x16 c) { return __builtin_amdgcn_mfma_f32_32x32x16_bf16(a, b, c, 0, 0, 0); }
; DI s16x4 tr_read(const char* p) { bfx4 r = __builtin_amdgcn_ds_read_tr16_b64_v4bf16((LDS_AS bfx4*)p); return __builtin_bit_cast(s16x4, r); }
; DI bf16x8 cat8(s16x4 lo, s16x4 hi) { return __builtin_shufflevector(lo, hi, 0, 1, 2, 3, 4, 5, 6, 7); }
; template <int BM, class Epi>
; DI void gemm_tile(const bf16_t* __restrict__ A, int lda, const bf16_t* __restrict__ B, int ldb, int K, int row0, int col0, const Epi& epi, char* smem) {
;     ...
;     for (int kt = 0; kt < nk; ++kt) {
;         const char* cur = smem + (kt & 1) * GSTAGE;
;         char* nxt = smem + ((kt & 1) ^ 1) * GSTAGE;
;         const bool w1 = kt + 1 < nk, l2 = kt + 2 < nk;
;         const bf16_t* a2 = ag + (size_t)(kt + 2) * 64; const bf16_t* b2 = bg + (size_t)(kt + 2) * 64 * ldb;
; #pragma unroll
;         for (int s = 0; s < 4; ++s) {
;             bf16x8 xf[MI], wf[2];
; #pragma unroll
;             for (int mi = 0; mi < MI; ++mi) xf[mi] = *(const bf16x8*)(cur + xoff + mi * 32 * GA_S + s * 32);
; #pragma unroll
;             for (int ni = 0; ni < 2; ++ni) {
;                 const char* wp = cur + woff + s * 16 * GB_S + ni * 64;
;                 wf[ni] = cat8(tr_read(wp), tr_read(wp + 4 * GB_S));
;             }
; #pragma unroll
;             for (int mi = 0; mi < MI; ++mi)
; #pragma unroll
;                 for (int ni = 0; ni < 2; ++ni) acc[mi][ni] = mfma32(wf[ni], xf[mi], acc[mi][ni]);
;             if (w1) {
;                 if (s < NA_) *(u32x4*)(nxt + aw + 64 * s * GA_S) = ra[s];
;                 *(u32x4*)(nxt + bw + 16 * s * GB_S) = rb[s];
;             }
;             if (l2) {
;                 if (s < NA_) ra[s] = *(const u32x4*)(a2 + (size_t)(64 * s) * lda);
;                 rb[s] = *(const u32x4*)(b2 + (size_t)(16 * s) * ldb);
;             }
;         }
	ds_read_b64_tr_b16 v[234:235], v149 offset:36864
	ds_read_b64_tr_b16 v[236:237], v149 offset:39168
	ds_read_b128 v[218:221], v148
	ds_read_b64_tr_b16 v[238:239], v149 offset:36928
	ds_read_b64_tr_b16 v[240:241], v149 offset:39232
	ds_read_b128 v[222:225], v148 offset:4608
	v_mfma_f32_32x32x16_bf16 v[32:47], v[242:245], v[226:229], v[32:47]
	v_mfma_f32_32x32x16_bf16 v[48:63], v[246:249], v[226:229], v[48:63]
	v_mfma_f32_32x32x16_bf16 v[0:15], v[242:245], v[230:233], v[0:15]
	v_mfma_f32_32x32x16_bf16 v[16:31], v[246:249], v[230:233], v[16:31]
	ds_read_b128 v[226:229], v148 offset:9216
	ds_read_b128 v[230:233], v148 offset:13824
	s_waitcnt lgkmcnt(5)
	v_mfma_f32_32x32x16_bf16 v[112:127], v[234:237], v[218:221], v[112:127]
	ds_read_b64_tr_b16 v[242:243], v149 offset:46080
	ds_read_b64_tr_b16 v[244:245], v149 offset:48384
	ds_read_b64_tr_b16 v[246:247], v149 offset:46144
	ds_read_b64_tr_b16 v[248:249], v149 offset:48448
	s_waitcnt lgkmcnt(7)
	v_mfma_f32_32x32x16_bf16 v[96:111], v[238:241], v[218:221], v[96:111]
	ds_read_b128 v[218:221], v148 offset:32
	s_waitcnt lgkmcnt(7)
	v_mfma_f32_32x32x16_bf16 v[80:95], v[234:237], v[222:225], v[80:95]
	v_mfma_f32_32x32x16_bf16 v[64:79], v[238:241], v[222:225], v[64:79]
	ds_read_b128 v[222:225], v148 offset:4640
	s_waitcnt vmcnt(3)
	ds_write_b128 v147, v[166:169]
	ds_write_b128 v146, v[132:135] offset:36864
	s_waitcnt lgkmcnt(9)
	v_mfma_f32_32x32x16_bf16 v[32:47], v[234:237], v[226:229], v[32:47]
	v_mfma_f32_32x32x16_bf16 v[48:63], v[238:241], v[226:229], v[48:63]
	ds_read_b128 v[226:229], v148 offset:9248
	s_waitcnt lgkmcnt(9)
	v_mfma_f32_32x32x16_bf16 v[0:15], v[234:237], v[230:233], v[0:15]
	v_mfma_f32_32x32x16_bf16 v[16:31], v[238:241], v[230:233], v[16:31]
	ds_read_b128 v[230:233], v148 offset:13856
	s_waitcnt vmcnt(2)
	ds_write_b128 v147, v[180:183] offset:9216
	ds_write_b128 v146, v[158:161] offset:46080
	s_waitcnt lgkmcnt(7)
	v_mfma_f32_32x32x16_bf16 v[112:127], v[242:245], v[218:221], v[112:127]
	ds_read_b64_tr_b16 v[234:235], v149 offset:55296
	ds_read_b64_tr_b16 v[236:237], v149 offset:57600
	ds_read_b64_tr_b16 v[238:239], v149 offset:55360
	ds_read_b64_tr_b16 v[240:241], v149 offset:57664
	v_mfma_f32_32x32x16_bf16 v[96:111], v[246:249], v[218:221], v[96:111]
	ds_read_b128 v[218:221], v148 offset:64
	s_waitcnt lgkmcnt(11)
	v_mfma_f32_32x32x16_bf16 v[80:95], v[242:245], v[222:225], v[80:95]
	v_mfma_f32_32x32x16_bf16 v[64:79], v[246:249], v[222:225], v[64:79]
	ds_read_b128 v[222:225], v148 offset:4672
	s_waitcnt vmcnt(1)
	ds_write_b128 v147, v[184:187] offset:18432
	ds_write_b128 v146, v[162:165] offset:55296
	s_waitcnt lgkmcnt(11)
	v_mfma_f32_32x32x16_bf16 v[32:47], v[242:245], v[226:229], v[32:47]
	v_mfma_f32_32x32x16_bf16 v[48:63], v[246:249], v[226:229], v[48:63]
	ds_read_b128 v[226:229], v148 offset:9280
	s_waitcnt lgkmcnt(11)
	v_mfma_f32_32x32x16_bf16 v[0:15], v[242:245], v[230:233], v[0:15]
	v_mfma_f32_32x32x16_bf16 v[16:31], v[246:249], v[230:233], v[16:31]
	ds_read_b128 v[230:233], v148 offset:13888
	s_waitcnt vmcnt(0)
	ds_write_b128 v147, v[188:191] offset:27648
	ds_write_b128 v146, v[128:131] offset:64512
	s_waitcnt lgkmcnt(7)
	v_mfma_f32_32x32x16_bf16 v[112:127], v[234:237], v[218:221], v[112:127]
	ds_read_b64_tr_b16 v[242:243], v149 offset:64512
	ds_read_b64_tr_b16 v[244:245], v150 offset:29952
	ds_read_b64_tr_b16 v[246:247], v149 offset:64576
	ds_read_b64_tr_b16 v[248:249], v150 offset:30016
	v_mfma_f32_32x32x16_bf16 v[96:111], v[238:241], v[218:221], v[96:111]
	ds_read_b128 v[218:221], v148 offset:96
	v_add_co_u32_e32 v128, vcc, s1, v144
	s_mov_b32 s1, 0x70c000
	s_nop 0
	v_addc_co_u32_e32 v129, vcc, 0, v145, vcc
	s_waitcnt lgkmcnt(11)
	v_mfma_f32_32x32x16_bf16 v[80:95], v[234:237], v[222:225], v[80:95]
	v_mfma_f32_32x32x16_bf16 v[64:79], v[238:241], v[222:225], v[64:79]
	ds_read_b128 v[222:225], v148 offset:4704
	v_add_co_u32_e32 v130, vcc, s1, v144
	s_nop 1
	v_addc_co_u32_e32 v131, vcc, 0, v145, vcc
	v_add_co_u32_e32 v154, vcc, s87, v144
	s_nop 1
	v_addc_co_u32_e32 v155, vcc, 0, v145, vcc
	s_waitcnt lgkmcnt(9)
	v_mfma_f32_32x32x16_bf16 v[32:47], v[234:237], v[226:229], v[32:47]
	v_mfma_f32_32x32x16_bf16 v[48:63], v[238:241], v[226:229], v[48:63]
	ds_read_b128 v[226:229], v148 offset:9312
	v_add_co_u32_e32 v166, vcc, s4, v144
	s_nop 1
	v_addc_co_u32_e32 v167, vcc, 0, v145, vcc
	global_load_dwordx4 v[132:135], v[128:129], off
	s_waitcnt lgkmcnt(9)
	v_mfma_f32_32x32x16_bf16 v[0:15], v[234:237], v[230:233], v[0:15]
	v_mfma_f32_32x32x16_bf16 v[16:31], v[238:241], v[230:233], v[16:31]
	ds_read_b128 v[230:233], v148 offset:13920
	global_load_dwordx4 v[158:161], v[130:131], off
	global_load_dwordx4 v[162:165], v[154:155], off
	s_waitcnt lgkmcnt(3)
	v_mfma_f32_32x32x16_bf16 v[112:127], v[242:245], v[218:221], v[112:127]
	v_mfma_f32_32x32x16_bf16 v[96:111], v[246:249], v[218:221], v[96:111]
	s_nop 0
	global_load_dwordx4 v[128:131], v[166:167], off
	s_nop 0
	global_load_dwordx4 v[166:169], v[136:137], off offset:1280
	s_waitcnt lgkmcnt(2)
	v_mfma_f32_32x32x16_bf16 v[80:95], v[242:245], v[222:225], v[80:95]
	v_mfma_f32_32x32x16_bf16 v[64:79], v[246:249], v[222:225], v[64:79]
	global_load_dwordx4 v[180:183], v[138:139], off offset:1280
	global_load_dwordx4 v[184:187], v[140:141], off offset:1280
	global_load_dwordx4 v[188:191], v[142:143], off offset:1280
	s_waitcnt lgkmcnt(0)
	s_barrier
; DI f32x16 mfma32(bf16x8 a, bf16x8 b, f32x16 c) { return __builtin_amdgcn_mfma_f32_32x32x16_bf16(a, b, c, 0, 0, 0); }
; DI s16x4 tr_read(const char* p) { bfx4 r = __builtin_amdgcn_ds_read_tr16_b64_v4bf16((LDS_AS bfx4*)p); return __builtin_bit_cast(s16x4, r); }
; DI bf16x8 cat8(s16x4 lo, s16x4 hi) { return __builtin_shufflevector(lo, hi, 0, 1, 2, 3, 4, 5, 6, 7); }
; template <int BM, class Epi>
; DI void gemm_tile(const bf16_t* __restrict__ A, int lda, const bf16_t* __restrict__ B, int ldb, int K, int row0, int col0, const Epi& epi, char* smem) {
;     ...
;     for (int kt = 0; kt < nk; ++kt) {
;         const char* cur = smem + (kt & 1) * GSTAGE;
;         char* nxt = smem + ((kt & 1) ^ 1) * GSTAGE;
;         const bool w1 = kt + 1 < nk, l2 = kt + 2 < nk;
;         const bf16_t* a2 = ag + (size_t)(kt + 2) * 64; const bf16_t* b2 = bg + (size_t)(kt + 2) * 64 * ldb;
; #pragma unroll
;         for (int s = 0; s < 4; ++s) {
;             bf16x8 xf[MI], wf[2];
; #pragma unroll
;             for (int mi = 0; mi < MI; ++mi) xf[mi] = *(const bf16x8*)(cur + xoff + mi * 32 * GA_S + s * 32);
; #pragma unroll
;             for (int ni = 0; ni < 2; ++ni) {
;                 const char* wp = cur + woff + s * 16 * GB_S + ni * 64;
;                 wf[ni] = cat8(tr_read(wp), tr_read(wp + 4 * GB_S));
;             }
; #pragma unroll
;             for (int mi = 0; mi < MI; ++mi)
; #pragma unroll
;                 for (int ni = 0; ni < 2; ++ni) acc[mi][ni] = mfma32(wf[ni], xf[mi], acc[mi][ni]);
;             if (w1) {
;                 if (s < NA_) *(u32x4*)(nxt + aw + 64 * s * GA_S) = ra[s];
;                 *(u32x4*)(nxt + bw + 16 * s * GB_S) = rb[s];
;             }
;             if (l2) {
;                 if (s < NA_) ra[s] = *(const u32x4*)(a2 + (size_t)(64 * s) * lda);
;                 rb[s] = *(const u32x4*)(b2 + (size_t)(16 * s) * ldb);
;             }
;         }
	ds_read_b64_tr_b16 v[234:235], v156 offset:36864
	ds_read_b64_tr_b16 v[236:237], v156 offset:39168
	ds_read_b128 v[218:221], v172
	ds_read_b64_tr_b16 v[238:239], v156 offset:36928
	ds_read_b64_tr_b16 v[240:241], v156 offset:39232
	ds_read_b128 v[222:225], v172 offset:4608
	v_mfma_f32_32x32x16_bf16 v[32:47], v[242:245], v[226:229], v[32:47]
	v_mfma_f32_32x32x16_bf16 v[48:63], v[246:249], v[226:229], v[48:63]
	v_mfma_f32_32x32x16_bf16 v[0:15], v[242:245], v[230:233], v[0:15]
	v_mfma_f32_32x32x16_bf16 v[16:31], v[246:249], v[230:233], v[16:31]
	ds_read_b128 v[226:229], v172 offset:9216
	ds_read_b128 v[230:233], v172 offset:13824
	s_waitcnt lgkmcnt(5)
	v_mfma_f32_32x32x16_bf16 v[112:127], v[234:237], v[218:221], v[112:127]
	ds_read_b64_tr_b16 v[242:243], v156 offset:46080
	ds_read_b64_tr_b16 v[244:245], v156 offset:48384
	ds_read_b64_tr_b16 v[246:247], v156 offset:46144
	ds_read_b64_tr_b16 v[248:249], v156 offset:48448
	s_waitcnt lgkmcnt(7)
	v_mfma_f32_32x32x16_bf16 v[96:111], v[238:241], v[218:221], v[96:111]
	ds_read_b128 v[218:221], v172 offset:32
	s_waitcnt lgkmcnt(7)
	v_mfma_f32_32x32x16_bf16 v[80:95], v[234:237], v[222:225], v[80:95]
	v_mfma_f32_32x32x16_bf16 v[64:79], v[238:241], v[222:225], v[64:79]
	ds_read_b128 v[222:225], v172 offset:4640
	s_waitcnt vmcnt(3)
	ds_write_b128 v151, v[166:169]
	ds_write_b128 v152, v[132:135] offset:36864
	s_waitcnt lgkmcnt(9)
	v_mfma_f32_32x32x16_bf16 v[32:47], v[234:237], v[226:229], v[32:47]
	v_mfma_f32_32x32x16_bf16 v[48:63], v[238:241], v[226:229], v[48:63]
	ds_read_b128 v[226:229], v172 offset:9248
	s_waitcnt lgkmcnt(9)
	v_mfma_f32_32x32x16_bf16 v[0:15], v[234:237], v[230:233], v[0:15]
	v_mfma_f32_32x32x16_bf16 v[16:31], v[238:241], v[230:233], v[16:31]
	ds_read_b128 v[230:233], v172 offset:13856
	s_waitcnt vmcnt(2)
	ds_write_b128 v151, v[180:183] offset:9216
	ds_write_b128 v152, v[158:161] offset:46080
	s_waitcnt lgkmcnt(7)
	v_mfma_f32_32x32x16_bf16 v[112:127], v[242:245], v[218:221], v[112:127]
	ds_read_b64_tr_b16 v[234:235], v156 offset:55296
	ds_read_b64_tr_b16 v[236:237], v156 offset:57600
	ds_read_b64_tr_b16 v[238:239], v156 offset:55360
	ds_read_b64_tr_b16 v[240:241], v156 offset:57664
	v_mfma_f32_32x32x16_bf16 v[96:111], v[246:249], v[218:221], v[96:111]
	ds_read_b128 v[218:221], v172 offset:64
	s_waitcnt lgkmcnt(11)
	v_mfma_f32_32x32x16_bf16 v[80:95], v[242:245], v[222:225], v[80:95]
	v_mfma_f32_32x32x16_bf16 v[64:79], v[246:249], v[222:225], v[64:79]
	ds_read_b128 v[222:225], v172 offset:4672
	s_waitcnt vmcnt(1)
	ds_write_b128 v151, v[184:187] offset:18432
	ds_write_b128 v152, v[162:165] offset:55296
	s_waitcnt lgkmcnt(11)
	v_mfma_f32_32x32x16_bf16 v[32:47], v[242:245], v[226:229], v[32:47]
	v_mfma_f32_32x32x16_bf16 v[48:63], v[246:249], v[226:229], v[48:63]
	ds_read_b128 v[226:229], v172 offset:9280
	s_waitcnt lgkmcnt(11)
	v_mfma_f32_32x32x16_bf16 v[0:15], v[242:245], v[230:233], v[0:15]
	v_mfma_f32_32x32x16_bf16 v[16:31], v[246:249], v[230:233], v[16:31]
	ds_read_b128 v[230:233], v172 offset:13888
	s_waitcnt vmcnt(0)
	ds_write_b128 v151, v[188:191] offset:27648
	ds_write_b128 v152, v[128:131] offset:64512
	s_waitcnt lgkmcnt(7)
	v_mfma_f32_32x32x16_bf16 v[112:127], v[234:237], v[218:221], v[112:127]
	ds_read_b64_tr_b16 v[242:243], v156 offset:64512
	ds_read_b64_tr_b16 v[244:245], v157 offset:29952
	ds_read_b64_tr_b16 v[246:247], v156 offset:64576
	ds_read_b64_tr_b16 v[248:249], v157 offset:30016
	v_mfma_f32_32x32x16_bf16 v[96:111], v[238:241], v[218:221], v[96:111]
	ds_read_b128 v[218:221], v172 offset:96
	v_add_co_u32_e32 v128, vcc, s5, v144
	s_nop 1
	v_addc_co_u32_e32 v129, vcc, 0, v145, vcc
	v_add_co_u32_e32 v130, vcc, s91, v144
	s_nop 1
	v_addc_co_u32_e32 v131, vcc, 0, v145, vcc
	s_waitcnt lgkmcnt(11)
	v_mfma_f32_32x32x16_bf16 v[80:95], v[234:237], v[222:225], v[80:95]
	v_mfma_f32_32x32x16_bf16 v[64:79], v[238:241], v[222:225], v[64:79]
	ds_read_b128 v[222:225], v172 offset:4704
	v_add_co_u32_e32 v154, vcc, s96, v144
	s_nop 1
	v_addc_co_u32_e32 v155, vcc, 0, v145, vcc
	v_add_co_u32_e32 v166, vcc, s36, v144
	s_nop 1
	v_addc_co_u32_e32 v167, vcc, 0, v145, vcc
	s_waitcnt lgkmcnt(9)
	v_mfma_f32_32x32x16_bf16 v[32:47], v[234:237], v[226:229], v[32:47]
	v_mfma_f32_32x32x16_bf16 v[48:63], v[238:241], v[226:229], v[48:63]
	ds_read_b128 v[226:229], v172 offset:9312
	global_load_dwordx4 v[132:135], v[128:129], off
	global_load_dwordx4 v[158:161], v[130:131], off
	s_waitcnt lgkmcnt(9)
	v_mfma_f32_32x32x16_bf16 v[0:15], v[234:237], v[230:233], v[0:15]
	v_mfma_f32_32x32x16_bf16 v[16:31], v[238:241], v[230:233], v[16:31]
	ds_read_b128 v[230:233], v172 offset:13920
	global_load_dwordx4 v[162:165], v[154:155], off
	s_nop 0
	global_load_dwordx4 v[128:131], v[166:167], off
	s_waitcnt lgkmcnt(3)
	v_mfma_f32_32x32x16_bf16 v[112:127], v[242:245], v[218:221], v[112:127]
	v_mfma_f32_32x32x16_bf16 v[96:111], v[246:249], v[218:221], v[96:111]
	s_nop 0
	global_load_dwordx4 v[166:169], v[136:137], off offset:1408
	global_load_dwordx4 v[180:183], v[138:139], off offset:1408
	s_waitcnt lgkmcnt(2)
	v_mfma_f32_32x32x16_bf16 v[80:95], v[242:245], v[222:225], v[80:95]
	v_mfma_f32_32x32x16_bf16 v[64:79], v[246:249], v[222:225], v[64:79]
	global_load_dwordx4 v[184:187], v[140:141], off offset:1408
	global_load_dwordx4 v[188:191], v[142:143], off offset:1408
	s_waitcnt lgkmcnt(0)
	s_barrier
; DI f32x16 mfma32(bf16x8 a, bf16x8 b, f32x16 c) { return __builtin_amdgcn_mfma_f32_32x32x16_bf16(a, b, c, 0, 0, 0); }
; DI s16x4 tr_read(const char* p) { bfx4 r = __builtin_amdgcn_ds_read_tr16_b64_v4bf16((LDS_AS bfx4*)p); return __builtin_bit_cast(s16x4, r); }
; DI bf16x8 cat8(s16x4 lo, s16x4 hi) { return __builtin_shufflevector(lo, hi, 0, 1, 2, 3, 4, 5, 6, 7); }
; template <int BM, class Epi>
; DI void gemm_tile(const bf16_t* __restrict__ A, int lda, const bf16_t* __restrict__ B, int ldb, int K, int row0, int col0, const Epi& epi, char* smem) {
;     ...
;     for (int kt = 0; kt < nk; ++kt) {
;         const char* cur = smem + (kt & 1) * GSTAGE;
;         char* nxt = smem + ((kt & 1) ^ 1) * GSTAGE;
;         const bool w1 = kt + 1 < nk, l2 = kt + 2 < nk;
;         const bf16_t* a2 = ag + (size_t)(kt + 2) * 64; const bf16_t* b2 = bg + (size_t)(kt + 2) * 64 * ldb;
; #pragma unroll
;         for (int s = 0; s < 4; ++s) {
;             bf16x8 xf[MI], wf[2];
; #pragma unroll
;             for (int mi = 0; mi < MI; ++mi) xf[mi] = *(const bf16x8*)(cur + xoff + mi * 32 * GA_S + s * 32);
; #pragma unroll
;             for (int ni = 0; ni < 2; ++ni) {
;                 const char* wp = cur + woff + s * 16 * GB_S + ni * 64;
;                 wf[ni] = cat8(tr_read(wp), tr_read(wp + 4 * GB_S));
;             }
; #pragma unroll
;             for (int mi = 0; mi < MI; ++mi)
; #pragma unroll
;                 for (int ni = 0; ni < 2; ++ni) acc[mi][ni] = mfma32(wf[ni], xf[mi], acc[mi][ni]);
;             if (w1) {
;                 if (s < NA_) *(u32x4*)(nxt + aw + 64 * s * GA_S) = ra[s];
;                 *(u32x4*)(nxt + bw + 16 * s * GB_S) = rb[s];
;             }
;             if (l2) {
;                 if (s < NA_) ra[s] = *(const u32x4*)(a2 + (size_t)(64 * s) * lda);
;                 rb[s] = *(const u32x4*)(b2 + (size_t)(16 * s) * ldb);
;             }
;         }
	ds_read_b64_tr_b16 v[234:235], v149 offset:36864
	ds_read_b64_tr_b16 v[236:237], v149 offset:39168
	ds_read_b128 v[218:221], v148
	ds_read_b64_tr_b16 v[238:239], v149 offset:36928
	ds_read_b64_tr_b16 v[240:241], v149 offset:39232
	ds_read_b128 v[222:225], v148 offset:4608
	v_mfma_f32_32x32x16_bf16 v[32:47], v[242:245], v[226:229], v[32:47]
	v_mfma_f32_32x32x16_bf16 v[48:63], v[246:249], v[226:229], v[48:63]
	v_mfma_f32_32x32x16_bf16 v[0:15], v[242:245], v[230:233], v[0:15]
	v_mfma_f32_32x32x16_bf16 v[16:31], v[246:249], v[230:233], v[16:31]
	ds_read_b128 v[226:229], v148 offset:9216
	ds_read_b128 v[230:233], v148 offset:13824
	s_waitcnt lgkmcnt(5)
	v_mfma_f32_32x32x16_bf16 v[112:127], v[234:237], v[218:221], v[112:127]
	ds_read_b64_tr_b16 v[242:243], v149 offset:46080
	ds_read_b64_tr_b16 v[244:245], v149 offset:48384
	ds_read_b64_tr_b16 v[246:247], v149 offset:46144
	ds_read_b64_tr_b16 v[248:249], v149 offset:48448
	s_waitcnt lgkmcnt(7)
	v_mfma_f32_32x32x16_bf16 v[96:111], v[238:241], v[218:221], v[96:111]
	ds_read_b128 v[218:221], v148 offset:32
	s_waitcnt lgkmcnt(7)
	v_mfma_f32_32x32x16_bf16 v[80:95], v[234:237], v[222:225], v[80:95]
	v_mfma_f32_32x32x16_bf16 v[64:79], v[238:241], v[222:225], v[64:79]
	ds_read_b128 v[222:225], v148 offset:4640
	s_waitcnt vmcnt(3)
	ds_write_b128 v147, v[166:169]
	ds_write_b128 v146, v[132:135] offset:36864
	s_waitcnt lgkmcnt(9)
	v_mfma_f32_32x32x16_bf16 v[32:47], v[234:237], v[226:229], v[32:47]
	v_mfma_f32_32x32x16_bf16 v[48:63], v[238:241], v[226:229], v[48:63]
	ds_read_b128 v[226:229], v148 offset:9248
	s_waitcnt lgkmcnt(9)
	v_mfma_f32_32x32x16_bf16 v[0:15], v[234:237], v[230:233], v[0:15]
	v_mfma_f32_32x32x16_bf16 v[16:31], v[238:241], v[230:233], v[16:31]
	ds_read_b128 v[230:233], v148 offset:13856
	s_waitcnt vmcnt(2)
	ds_write_b128 v147, v[180:183] offset:9216
	ds_write_b128 v146, v[158:161] offset:46080
	s_waitcnt lgkmcnt(7)
	v_mfma_f32_32x32x16_bf16 v[112:127], v[242:245], v[218:221], v[112:127]
	ds_read_b64_tr_b16 v[234:235], v149 offset:55296
	ds_read_b64_tr_b16 v[236:237], v149 offset:57600
	ds_read_b64_tr_b16 v[238:239], v149 offset:55360
	ds_read_b64_tr_b16 v[240:241], v149 offset:57664
	v_mfma_f32_32x32x16_bf16 v[96:111], v[246:249], v[218:221], v[96:111]
	ds_read_b128 v[218:221], v148 offset:64
	s_waitcnt lgkmcnt(11)
	v_mfma_f32_32x32x16_bf16 v[80:95], v[242:245], v[222:225], v[80:95]
	v_mfma_f32_32x32x16_bf16 v[64:79], v[246:249], v[222:225], v[64:79]
	ds_read_b128 v[222:225], v148 offset:4672
	s_waitcnt vmcnt(1)
	ds_write_b128 v147, v[184:187] offset:18432
	ds_write_b128 v146, v[162:165] offset:55296
	s_waitcnt lgkmcnt(11)
	v_mfma_f32_32x32x16_bf16 v[32:47], v[242:245], v[226:229], v[32:47]
	v_mfma_f32_32x32x16_bf16 v[48:63], v[246:249], v[226:229], v[48:63]
	ds_read_b128 v[226:229], v148 offset:9280
	s_waitcnt lgkmcnt(11)
	v_mfma_f32_32x32x16_bf16 v[0:15], v[242:245], v[230:233], v[0:15]
	v_mfma_f32_32x32x16_bf16 v[16:31], v[246:249], v[230:233], v[16:31]
	ds_read_b128 v[230:233], v148 offset:13888
	s_waitcnt vmcnt(0)
	ds_write_b128 v147, v[188:191] offset:27648
	ds_write_b128 v146, v[128:131] offset:64512
	s_waitcnt lgkmcnt(7)
	v_mfma_f32_32x32x16_bf16 v[112:127], v[234:237], v[218:221], v[112:127]
	ds_read_b64_tr_b16 v[242:243], v149 offset:64512
	ds_read_b64_tr_b16 v[244:245], v150 offset:29952
	ds_read_b64_tr_b16 v[246:247], v149 offset:64576
	ds_read_b64_tr_b16 v[248:249], v150 offset:30016
	v_mfma_f32_32x32x16_bf16 v[96:111], v[238:241], v[218:221], v[96:111]
	ds_read_b128 v[218:221], v148 offset:96
	v_add_co_u32_e32 v128, vcc, s97, v144
	s_nop 1
	v_addc_co_u32_e32 v129, vcc, 0, v145, vcc
	v_add_co_u32_e32 v130, vcc, s3, v144
	s_nop 1
	v_addc_co_u32_e32 v131, vcc, 0, v145, vcc
	s_waitcnt lgkmcnt(11)
	v_mfma_f32_32x32x16_bf16 v[80:95], v[234:237], v[222:225], v[80:95]
	v_mfma_f32_32x32x16_bf16 v[64:79], v[238:241], v[222:225], v[64:79]
	ds_read_b128 v[222:225], v148 offset:4704
	v_add_co_u32_e32 v154, vcc, s19, v144
	s_nop 1
	v_addc_co_u32_e32 v155, vcc, 0, v145, vcc
	v_add_co_u32_e32 v166, vcc, s22, v144
	s_nop 1
	v_addc_co_u32_e32 v167, vcc, 0, v145, vcc
	s_waitcnt lgkmcnt(9)
	v_mfma_f32_32x32x16_bf16 v[32:47], v[234:237], v[226:229], v[32:47]
	v_mfma_f32_32x32x16_bf16 v[48:63], v[238:241], v[226:229], v[48:63]
	ds_read_b128 v[226:229], v148 offset:9312
	global_load_dwordx4 v[132:135], v[128:129], off
	global_load_dwordx4 v[158:161], v[130:131], off
	s_waitcnt lgkmcnt(9)
	v_mfma_f32_32x32x16_bf16 v[0:15], v[234:237], v[230:233], v[0:15]
	v_mfma_f32_32x32x16_bf16 v[16:31], v[238:241], v[230:233], v[16:31]
	ds_read_b128 v[230:233], v148 offset:13920
	global_load_dwordx4 v[162:165], v[154:155], off
	s_nop 0
	global_load_dwordx4 v[128:131], v[166:167], off
	s_waitcnt lgkmcnt(3)
	v_mfma_f32_32x32x16_bf16 v[112:127], v[242:245], v[218:221], v[112:127]
	v_mfma_f32_32x32x16_bf16 v[96:111], v[246:249], v[218:221], v[96:111]
	s_nop 0
	global_load_dwordx4 v[166:169], v[136:137], off offset:1536
	global_load_dwordx4 v[180:183], v[138:139], off offset:1536
	s_waitcnt lgkmcnt(2)
	v_mfma_f32_32x32x16_bf16 v[80:95], v[242:245], v[222:225], v[80:95]
	v_mfma_f32_32x32x16_bf16 v[64:79], v[246:249], v[222:225], v[64:79]
	global_load_dwordx4 v[184:187], v[140:141], off offset:1536
	global_load_dwordx4 v[188:191], v[142:143], off offset:1536
	s_waitcnt lgkmcnt(0)
	s_barrier
; DI f32x16 mfma32(bf16x8 a, bf16x8 b, f32x16 c) { return __builtin_amdgcn_mfma_f32_32x32x16_bf16(a, b, c, 0, 0, 0); }
; DI s16x4 tr_read(const char* p) { bfx4 r = __builtin_amdgcn_ds_read_tr16_b64_v4bf16((LDS_AS bfx4*)p); return __builtin_bit_cast(s16x4, r); }
; DI bf16x8 cat8(s16x4 lo, s16x4 hi) { return __builtin_shufflevector(lo, hi, 0, 1, 2, 3, 4, 5, 6, 7); }
; template <int BM, class Epi>
; DI void gemm_tile(const bf16_t* __restrict__ A, int lda, const bf16_t* __restrict__ B, int ldb, int K, int row0, int col0, const Epi& epi, char* smem) {
;     ...
;     for (int kt = 0; kt < nk; ++kt) {
;         const char* cur = smem + (kt & 1) * GSTAGE;
;         char* nxt = smem + ((kt & 1) ^ 1) * GSTAGE;
;         const bool w1 = kt + 1 < nk, l2 = kt + 2 < nk;
;         const bf16_t* a2 = ag + (size_t)(kt + 2) * 64; const bf16_t* b2 = bg + (size_t)(kt + 2) * 64 * ldb;
; #pragma unroll
;         for (int s = 0; s < 4; ++s) {
;             bf16x8 xf[MI], wf[2];
; #pragma unroll
;             for (int mi = 0; mi < MI; ++mi) xf[mi] = *(const bf16x8*)(cur + xoff + mi * 32 * GA_S + s * 32);
; #pragma unroll
;             for (int ni = 0; ni < 2; ++ni) {
;                 const char* wp = cur + woff + s * 16 * GB_S + ni * 64;
;                 wf[ni] = cat8(tr_read(wp), tr_read(wp + 4 * GB_S));
;             }
; #pragma unroll
;             for (int mi = 0; mi < MI; ++mi)
; #pragma unroll
;                 for (int ni = 0; ni < 2; ++ni) acc[mi][ni] = mfma32(wf[ni], xf[mi], acc[mi][ni]);
;             if (w1) {
;                 if (s < NA_) *(u32x4*)(nxt + aw + 64 * s * GA_S) = ra[s];
;                 *(u32x4*)(nxt + bw + 16 * s * GB_S) = rb[s];
;             }
;             if (l2) {
;                 if (s < NA_) ra[s] = *(const u32x4*)(a2 + (size_t)(64 * s) * lda);
;                 rb[s] = *(const u32x4*)(b2 + (size_t)(16 * s) * ldb);
;             }
;         }
	ds_read_b64_tr_b16 v[234:235], v156 offset:36864
	ds_read_b64_tr_b16 v[236:237], v156 offset:39168
	ds_read_b128 v[218:221], v172
	ds_read_b64_tr_b16 v[238:239], v156 offset:36928
	ds_read_b64_tr_b16 v[240:241], v156 offset:39232
	ds_read_b128 v[222:225], v172 offset:4608
	v_mfma_f32_32x32x16_bf16 v[32:47], v[242:245], v[226:229], v[32:47]
	v_mfma_f32_32x32x16_bf16 v[48:63], v[246:249], v[226:229], v[48:63]
	v_mfma_f32_32x32x16_bf16 v[0:15], v[242:245], v[230:233], v[0:15]
	v_mfma_f32_32x32x16_bf16 v[16:31], v[246:249], v[230:233], v[16:31]
	ds_read_b128 v[226:229], v172 offset:9216
	ds_read_b128 v[230:233], v172 offset:13824
	s_waitcnt lgkmcnt(5)
	v_mfma_f32_32x32x16_bf16 v[112:127], v[234:237], v[218:221], v[112:127]
	ds_read_b64_tr_b16 v[242:243], v156 offset:46080
	ds_read_b64_tr_b16 v[244:245], v156 offset:48384
	ds_read_b64_tr_b16 v[246:247], v156 offset:46144
	ds_read_b64_tr_b16 v[248:249], v156 offset:48448
	s_waitcnt lgkmcnt(7)
	v_mfma_f32_32x32x16_bf16 v[96:111], v[238:241], v[218:221], v[96:111]
	ds_read_b128 v[218:221], v172 offset:32
	s_waitcnt lgkmcnt(7)
	v_mfma_f32_32x32x16_bf16 v[80:95], v[234:237], v[222:225], v[80:95]
	v_mfma_f32_32x32x16_bf16 v[64:79], v[238:241], v[222:225], v[64:79]
	ds_read_b128 v[222:225], v172 offset:4640
	s_waitcnt vmcnt(3)
	ds_write_b128 v151, v[166:169]
	ds_write_b128 v152, v[132:135] offset:36864
	s_waitcnt lgkmcnt(9)
	v_mfma_f32_32x32x16_bf16 v[32:47], v[234:237], v[226:229], v[32:47]
	v_mfma_f32_32x32x16_bf16 v[48:63], v[238:241], v[226:229], v[48:63]
	ds_read_b128 v[226:229], v172 offset:9248
	s_waitcnt lgkmcnt(9)
	v_mfma_f32_32x32x16_bf16 v[0:15], v[234:237], v[230:233], v[0:15]
	v_mfma_f32_32x32x16_bf16 v[16:31], v[238:241], v[230:233], v[16:31]
	ds_read_b128 v[230:233], v172 offset:13856
	s_waitcnt vmcnt(2)
	ds_write_b128 v151, v[180:183] offset:9216
	ds_write_b128 v152, v[158:161] offset:46080
	s_waitcnt lgkmcnt(7)
	v_mfma_f32_32x32x16_bf16 v[112:127], v[242:245], v[218:221], v[112:127]
	ds_read_b64_tr_b16 v[234:235], v156 offset:55296
	ds_read_b64_tr_b16 v[236:237], v156 offset:57600
	ds_read_b64_tr_b16 v[238:239], v156 offset:55360
	ds_read_b64_tr_b16 v[240:241], v156 offset:57664
	v_mfma_f32_32x32x16_bf16 v[96:111], v[246:249], v[218:221], v[96:111]
	ds_read_b128 v[218:221], v172 offset:64
	s_waitcnt lgkmcnt(11)
	v_mfma_f32_32x32x16_bf16 v[80:95], v[242:245], v[222:225], v[80:95]
	v_mfma_f32_32x32x16_bf16 v[64:79], v[246:249], v[222:225], v[64:79]
	ds_read_b128 v[222:225], v172 offset:4672
	s_waitcnt vmcnt(1)
	ds_write_b128 v151, v[184:187] offset:18432
	ds_write_b128 v152, v[162:165] offset:55296
	s_waitcnt lgkmcnt(11)
	v_mfma_f32_32x32x16_bf16 v[32:47], v[242:245], v[226:229], v[32:47]
	v_mfma_f32_32x32x16_bf16 v[48:63], v[246:249], v[226:229], v[48:63]
	ds_read_b128 v[226:229], v172 offset:9280
	s_waitcnt lgkmcnt(11)
	v_mfma_f32_32x32x16_bf16 v[0:15], v[242:245], v[230:233], v[0:15]
	v_mfma_f32_32x32x16_bf16 v[16:31], v[246:249], v[230:233], v[16:31]
	ds_read_b128 v[230:233], v172 offset:13888
	s_waitcnt vmcnt(0)
	ds_write_b128 v151, v[188:191] offset:27648
	ds_write_b128 v152, v[128:131] offset:64512
	s_waitcnt lgkmcnt(7)
	v_mfma_f32_32x32x16_bf16 v[112:127], v[234:237], v[218:221], v[112:127]
	ds_read_b64_tr_b16 v[242:243], v156 offset:64512
	ds_read_b64_tr_b16 v[244:245], v157 offset:29952
	ds_read_b64_tr_b16 v[246:247], v156 offset:64576
	ds_read_b64_tr_b16 v[248:249], v157 offset:30016
	v_mfma_f32_32x32x16_bf16 v[96:111], v[238:241], v[218:221], v[96:111]
	ds_read_b128 v[218:221], v172 offset:96
	v_add_co_u32_e32 v128, vcc, s82, v144
	s_nop 1
	v_addc_co_u32_e32 v129, vcc, 0, v145, vcc
	v_add_co_u32_e32 v130, vcc, s83, v144
	s_nop 1
	v_addc_co_u32_e32 v131, vcc, 0, v145, vcc
	s_waitcnt lgkmcnt(11)
	v_mfma_f32_32x32x16_bf16 v[80:95], v[234:237], v[222:225], v[80:95]
	v_mfma_f32_32x32x16_bf16 v[64:79], v[238:241], v[222:225], v[64:79]
	ds_read_b128 v[222:225], v172 offset:4704
	v_add_co_u32_e32 v154, vcc, s20, v144
	s_nop 1
	v_addc_co_u32_e32 v155, vcc, 0, v145, vcc
	v_add_co_u32_e32 v166, vcc, s23, v144
	s_nop 1
	v_addc_co_u32_e32 v167, vcc, 0, v145, vcc
	s_waitcnt lgkmcnt(9)
	v_mfma_f32_32x32x16_bf16 v[32:47], v[234:237], v[226:229], v[32:47]
	v_mfma_f32_32x32x16_bf16 v[48:63], v[238:241], v[226:229], v[48:63]
	ds_read_b128 v[226:229], v172 offset:9312
	global_load_dwordx4 v[132:135], v[128:129], off
	global_load_dwordx4 v[158:161], v[130:131], off
	s_waitcnt lgkmcnt(9)
	v_mfma_f32_32x32x16_bf16 v[0:15], v[234:237], v[230:233], v[0:15]
	v_mfma_f32_32x32x16_bf16 v[16:31], v[238:241], v[230:233], v[16:31]
	ds_read_b128 v[230:233], v172 offset:13920
	global_load_dwordx4 v[162:165], v[154:155], off
	s_nop 0
	global_load_dwordx4 v[128:131], v[166:167], off
	s_waitcnt lgkmcnt(3)
	v_mfma_f32_32x32x16_bf16 v[112:127], v[242:245], v[218:221], v[112:127]
	v_mfma_f32_32x32x16_bf16 v[96:111], v[246:249], v[218:221], v[96:111]
	s_nop 0
	global_load_dwordx4 v[166:169], v[136:137], off offset:1664
	global_load_dwordx4 v[180:183], v[138:139], off offset:1664
	s_waitcnt lgkmcnt(2)
	v_mfma_f32_32x32x16_bf16 v[80:95], v[242:245], v[222:225], v[80:95]
	v_mfma_f32_32x32x16_bf16 v[64:79], v[246:249], v[222:225], v[64:79]
	global_load_dwordx4 v[184:187], v[140:141], off offset:1664
	global_load_dwordx4 v[188:191], v[142:143], off offset:1664
	s_waitcnt lgkmcnt(0)
	s_barrier
; DI f32x16 mfma32(bf16x8 a, bf16x8 b, f32x16 c) { return __builtin_amdgcn_mfma_f32_32x32x16_bf16(a, b, c, 0, 0, 0); }
; DI s16x4 tr_read(const char* p) { bfx4 r = __builtin_amdgcn_ds_read_tr16_b64_v4bf16((LDS_AS bfx4*)p); return __builtin_bit_cast(s16x4, r); }
; DI bf16x8 cat8(s16x4 lo, s16x4 hi) { return __builtin_shufflevector(lo, hi, 0, 1, 2, 3, 4, 5, 6, 7); }
; template <int BM, class Epi>
; DI void gemm_tile(const bf16_t* __restrict__ A, int lda, const bf16_t* __restrict__ B, int ldb, int K, int row0, int col0, const Epi& epi, char* smem) {
;     ...
;     for (int kt = 0; kt < nk; ++kt) {
;         const char* cur = smem + (kt & 1) * GSTAGE;
;         char* nxt = smem + ((kt & 1) ^ 1) * GSTAGE;
;         const bool w1 = kt + 1 < nk, l2 = kt + 2 < nk;
;         const bf16_t* a2 = ag + (size_t)(kt + 2) * 64; const bf16_t* b2 = bg + (size_t)(kt + 2) * 64 * ldb;
; #pragma unroll
;         for (int s = 0; s < 4; ++s) {
;             bf16x8 xf[MI], wf[2];
; #pragma unroll
;             for (int mi = 0; mi < MI; ++mi) xf[mi] = *(const bf16x8*)(cur + xoff + mi * 32 * GA_S + s * 32);
; #pragma unroll
;             for (int ni = 0; ni < 2; ++ni) {
;                 const char* wp = cur + woff + s * 16 * GB_S + ni * 64;
;                 wf[ni] = cat8(tr_read(wp), tr_read(wp + 4 * GB_S));
;             }
; #pragma unroll
;             for (int mi = 0; mi < MI; ++mi)
; #pragma unroll
;                 for (int ni = 0; ni < 2; ++ni) acc[mi][ni] = mfma32(wf[ni], xf[mi], acc[mi][ni]);
;             if (w1) {
;                 if (s < NA_) *(u32x4*)(nxt + aw + 64 * s * GA_S) = ra[s];
;                 *(u32x4*)(nxt + bw + 16 * s * GB_S) = rb[s];
;             }
;             if (l2) {
;                 if (s < NA_) ra[s] = *(const u32x4*)(a2 + (size_t)(64 * s) * lda);
;                 rb[s] = *(const u32x4*)(b2 + (size_t)(16 * s) * ldb);
;             }
;         }
	ds_read_b64_tr_b16 v[234:235], v149 offset:36864
	ds_read_b64_tr_b16 v[236:237], v149 offset:39168
	ds_read_b128 v[218:221], v148
	ds_read_b64_tr_b16 v[238:239], v149 offset:36928
	ds_read_b64_tr_b16 v[240:241], v149 offset:39232
	ds_read_b128 v[222:225], v148 offset:4608
	v_mfma_f32_32x32x16_bf16 v[32:47], v[242:245], v[226:229], v[32:47]
	v_mfma_f32_32x32x16_bf16 v[48:63], v[246:249], v[226:229], v[48:63]
	v_mfma_f32_32x32x16_bf16 v[0:15], v[242:245], v[230:233], v[0:15]
	v_mfma_f32_32x32x16_bf16 v[16:31], v[246:249], v[230:233], v[16:31]
	ds_read_b128 v[226:229], v148 offset:9216
	ds_read_b128 v[230:233], v148 offset:13824
	s_waitcnt lgkmcnt(5)
	v_mfma_f32_32x32x16_bf16 v[112:127], v[234:237], v[218:221], v[112:127]
	ds_read_b64_tr_b16 v[242:243], v149 offset:46080
	ds_read_b64_tr_b16 v[244:245], v149 offset:48384
	ds_read_b64_tr_b16 v[246:247], v149 offset:46144
	ds_read_b64_tr_b16 v[248:249], v149 offset:48448
	s_waitcnt lgkmcnt(7)
	v_mfma_f32_32x32x16_bf16 v[96:111], v[238:241], v[218:221], v[96:111]
	ds_read_b128 v[218:221], v148 offset:32
	s_waitcnt lgkmcnt(7)
	v_mfma_f32_32x32x16_bf16 v[80:95], v[234:237], v[222:225], v[80:95]
	v_mfma_f32_32x32x16_bf16 v[64:79], v[238:241], v[222:225], v[64:79]
	ds_read_b128 v[222:225], v148 offset:4640
	s_waitcnt vmcnt(3)
	ds_write_b128 v147, v[166:169]
	ds_write_b128 v146, v[132:135] offset:36864
	s_waitcnt lgkmcnt(9)
	v_mfma_f32_32x32x16_bf16 v[32:47], v[234:237], v[226:229], v[32:47]
	v_mfma_f32_32x32x16_bf16 v[48:63], v[238:241], v[226:229], v[48:63]
	ds_read_b128 v[226:229], v148 offset:9248
	s_waitcnt lgkmcnt(9)
	v_mfma_f32_32x32x16_bf16 v[0:15], v[234:237], v[230:233], v[0:15]
	v_mfma_f32_32x32x16_bf16 v[16:31], v[238:241], v[230:233], v[16:31]
	ds_read_b128 v[230:233], v148 offset:13856
	s_waitcnt vmcnt(2)
	ds_write_b128 v147, v[180:183] offset:9216
	ds_write_b128 v146, v[158:161] offset:46080
	s_waitcnt lgkmcnt(7)
	v_mfma_f32_32x32x16_bf16 v[112:127], v[242:245], v[218:221], v[112:127]
	ds_read_b64_tr_b16 v[234:235], v149 offset:55296
	ds_read_b64_tr_b16 v[236:237], v149 offset:57600
	ds_read_b64_tr_b16 v[238:239], v149 offset:55360
	ds_read_b64_tr_b16 v[240:241], v149 offset:57664
	v_mfma_f32_32x32x16_bf16 v[96:111], v[246:249], v[218:221], v[96:111]
	ds_read_b128 v[218:221], v148 offset:64
	s_waitcnt lgkmcnt(11)
	v_mfma_f32_32x32x16_bf16 v[80:95], v[242:245], v[222:225], v[80:95]
	v_mfma_f32_32x32x16_bf16 v[64:79], v[246:249], v[222:225], v[64:79]
	ds_read_b128 v[222:225], v148 offset:4672
	s_waitcnt vmcnt(1)
	ds_write_b128 v147, v[184:187] offset:18432
	ds_write_b128 v146, v[162:165] offset:55296
	s_waitcnt lgkmcnt(11)
	v_mfma_f32_32x32x16_bf16 v[32:47], v[242:245], v[226:229], v[32:47]
	v_mfma_f32_32x32x16_bf16 v[48:63], v[246:249], v[226:229], v[48:63]
	ds_read_b128 v[226:229], v148 offset:9280
	s_waitcnt lgkmcnt(11)
	v_mfma_f32_32x32x16_bf16 v[0:15], v[242:245], v[230:233], v[0:15]
	v_mfma_f32_32x32x16_bf16 v[16:31], v[246:249], v[230:233], v[16:31]
	ds_read_b128 v[230:233], v148 offset:13888
	s_waitcnt vmcnt(0)
	ds_write_b128 v147, v[188:191] offset:27648
	ds_write_b128 v146, v[128:131] offset:64512
	s_waitcnt lgkmcnt(7)
	v_mfma_f32_32x32x16_bf16 v[112:127], v[234:237], v[218:221], v[112:127]
	ds_read_b64_tr_b16 v[242:243], v149 offset:64512
	ds_read_b64_tr_b16 v[244:245], v150 offset:29952
	ds_read_b64_tr_b16 v[246:247], v149 offset:64576
	ds_read_b64_tr_b16 v[248:249], v150 offset:30016
	v_mfma_f32_32x32x16_bf16 v[96:111], v[238:241], v[218:221], v[96:111]
	ds_read_b128 v[218:221], v148 offset:96
	v_add_co_u32_e32 v128, vcc, s24, v144
	s_nop 1
	v_addc_co_u32_e32 v129, vcc, 0, v145, vcc
	v_add_co_u32_e32 v130, vcc, s25, v144
	s_nop 1
	v_addc_co_u32_e32 v131, vcc, 0, v145, vcc
	s_waitcnt lgkmcnt(11)
	v_mfma_f32_32x32x16_bf16 v[80:95], v[234:237], v[222:225], v[80:95]
	v_mfma_f32_32x32x16_bf16 v[64:79], v[238:241], v[222:225], v[64:79]
	ds_read_b128 v[222:225], v148 offset:4704
	v_add_co_u32_e32 v132, vcc, s26, v144
	s_nop 1
	v_addc_co_u32_e32 v133, vcc, 0, v145, vcc
	v_add_co_u32_e32 v134, vcc, s28, v144
	s_nop 0
	v_addc_co_u32_e32 v135, vcc, 0, v145, vcc
	s_waitcnt lgkmcnt(9)
	v_mfma_f32_32x32x16_bf16 v[32:47], v[234:237], v[226:229], v[32:47]
	v_mfma_f32_32x32x16_bf16 v[48:63], v[238:241], v[226:229], v[48:63]
	ds_read_b128 v[226:229], v148 offset:9312
	global_load_dwordx4 v[158:161], v[128:129], off
	global_load_dwordx4 v[162:165], v[130:131], off
	s_waitcnt lgkmcnt(9)
	v_mfma_f32_32x32x16_bf16 v[0:15], v[234:237], v[230:233], v[0:15]
	v_mfma_f32_32x32x16_bf16 v[16:31], v[238:241], v[230:233], v[16:31]
	ds_read_b128 v[230:233], v148 offset:13920
	global_load_dwordx4 v[166:169], v[132:133], off
	s_nop 0
	global_load_dwordx4 v[128:131], v[134:135], off
	s_waitcnt lgkmcnt(3)
	v_mfma_f32_32x32x16_bf16 v[112:127], v[242:245], v[218:221], v[112:127]
	v_mfma_f32_32x32x16_bf16 v[96:111], v[246:249], v[218:221], v[96:111]
	global_load_dwordx4 v[180:183], v[136:137], off offset:1792
	global_load_dwordx4 v[184:187], v[138:139], off offset:1792
	s_waitcnt lgkmcnt(2)
	v_mfma_f32_32x32x16_bf16 v[80:95], v[242:245], v[222:225], v[80:95]
	v_mfma_f32_32x32x16_bf16 v[64:79], v[246:249], v[222:225], v[64:79]
	global_load_dwordx4 v[188:191], v[140:141], off offset:1792
	s_nop 0
	global_load_dwordx4 v[132:135], v[142:143], off offset:1792
	s_waitcnt lgkmcnt(0)
	s_barrier
; DI f32x16 mfma32(bf16x8 a, bf16x8 b, f32x16 c) { return __builtin_amdgcn_mfma_f32_32x32x16_bf16(a, b, c, 0, 0, 0); }
; DI s16x4 tr_read(const char* p) { bfx4 r = __builtin_amdgcn_ds_read_tr16_b64_v4bf16((LDS_AS bfx4*)p); return __builtin_bit_cast(s16x4, r); }
; DI bf16x8 cat8(s16x4 lo, s16x4 hi) { return __builtin_shufflevector(lo, hi, 0, 1, 2, 3, 4, 5, 6, 7); }
; template <int BM, class Epi>
; DI void gemm_tile(const bf16_t* __restrict__ A, int lda, const bf16_t* __restrict__ B, int ldb, int K, int row0, int col0, const Epi& epi, char* smem) {
;     ...
;     for (int kt = 0; kt < nk; ++kt) {
;         const char* cur = smem + (kt & 1) * GSTAGE;
;         char* nxt = smem + ((kt & 1) ^ 1) * GSTAGE;
;         const bool w1 = kt + 1 < nk, l2 = kt + 2 < nk;
;         const bf16_t* a2 = ag + (size_t)(kt + 2) * 64; const bf16_t* b2 = bg + (size_t)(kt + 2) * 64 * ldb;
; #pragma unroll
;         for (int s = 0; s < 4; ++s) {
;             bf16x8 xf[MI], wf[2];
; #pragma unroll
;             for (int mi = 0; mi < MI; ++mi) xf[mi] = *(const bf16x8*)(cur + xoff + mi * 32 * GA_S + s * 32);
; #pragma unroll
;             for (int ni = 0; ni < 2; ++ni) {
;                 const char* wp = cur + woff + s * 16 * GB_S + ni * 64;
;                 wf[ni] = cat8(tr_read(wp), tr_read(wp + 4 * GB_S));
;             }
; #pragma unroll
;             for (int mi = 0; mi < MI; ++mi)
; #pragma unroll
;                 for (int ni = 0; ni < 2; ++ni) acc[mi][ni] = mfma32(wf[ni], xf[mi], acc[mi][ni]);
;             if (w1) {
;                 if (s < NA_) *(u32x4*)(nxt + aw + 64 * s * GA_S) = ra[s];
;                 *(u32x4*)(nxt + bw + 16 * s * GB_S) = rb[s];
;             }
;             if (l2) {
;                 if (s < NA_) ra[s] = *(const u32x4*)(a2 + (size_t)(64 * s) * lda);
;                 rb[s] = *(const u32x4*)(b2 + (size_t)(16 * s) * ldb);
;             }
;         }
	ds_read_b64_tr_b16 v[234:235], v156 offset:36864
	ds_read_b64_tr_b16 v[236:237], v156 offset:39168
	ds_read_b128 v[218:221], v172
	ds_read_b64_tr_b16 v[238:239], v156 offset:36928
	ds_read_b64_tr_b16 v[240:241], v156 offset:39232
	ds_read_b128 v[222:225], v172 offset:4608
	v_mfma_f32_32x32x16_bf16 v[32:47], v[242:245], v[226:229], v[32:47]
	v_mfma_f32_32x32x16_bf16 v[48:63], v[246:249], v[226:229], v[48:63]
	v_mfma_f32_32x32x16_bf16 v[0:15], v[242:245], v[230:233], v[0:15]
	v_mfma_f32_32x32x16_bf16 v[16:31], v[246:249], v[230:233], v[16:31]
	ds_read_b128 v[226:229], v172 offset:9216
	ds_read_b128 v[230:233], v172 offset:13824
	s_waitcnt lgkmcnt(5)
	v_mfma_f32_32x32x16_bf16 v[112:127], v[234:237], v[218:221], v[112:127]
	ds_read_b64_tr_b16 v[242:243], v156 offset:46080
	ds_read_b64_tr_b16 v[244:245], v156 offset:48384
	ds_read_b64_tr_b16 v[246:247], v156 offset:46144
	ds_read_b64_tr_b16 v[248:249], v156 offset:48448
	s_waitcnt lgkmcnt(7)
	v_mfma_f32_32x32x16_bf16 v[96:111], v[238:241], v[218:221], v[96:111]
	ds_read_b128 v[218:221], v172 offset:32
	s_waitcnt lgkmcnt(7)
	v_mfma_f32_32x32x16_bf16 v[80:95], v[234:237], v[222:225], v[80:95]
	v_mfma_f32_32x32x16_bf16 v[64:79], v[238:241], v[222:225], v[64:79]
	ds_read_b128 v[222:225], v172 offset:4640
	s_waitcnt vmcnt(3)
	ds_write_b128 v151, v[180:183]
	ds_write_b128 v152, v[158:161] offset:36864
	s_waitcnt lgkmcnt(9)
	v_mfma_f32_32x32x16_bf16 v[32:47], v[234:237], v[226:229], v[32:47]
	v_mfma_f32_32x32x16_bf16 v[48:63], v[238:241], v[226:229], v[48:63]
	ds_read_b128 v[226:229], v172 offset:9248
	s_waitcnt lgkmcnt(9)
	v_mfma_f32_32x32x16_bf16 v[0:15], v[234:237], v[230:233], v[0:15]
	v_mfma_f32_32x32x16_bf16 v[16:31], v[238:241], v[230:233], v[16:31]
	ds_read_b128 v[230:233], v172 offset:13856
	s_waitcnt vmcnt(2)
	ds_write_b128 v151, v[184:187] offset:9216
	ds_write_b128 v152, v[162:165] offset:46080
	s_waitcnt lgkmcnt(7)
	v_mfma_f32_32x32x16_bf16 v[112:127], v[242:245], v[218:221], v[112:127]
	ds_read_b64_tr_b16 v[234:235], v156 offset:55296
	ds_read_b64_tr_b16 v[236:237], v156 offset:57600
	ds_read_b64_tr_b16 v[238:239], v156 offset:55360
	ds_read_b64_tr_b16 v[240:241], v156 offset:57664
	v_mfma_f32_32x32x16_bf16 v[96:111], v[246:249], v[218:221], v[96:111]
	ds_read_b128 v[218:221], v172 offset:64
	s_waitcnt lgkmcnt(11)
	v_mfma_f32_32x32x16_bf16 v[80:95], v[242:245], v[222:225], v[80:95]
	v_mfma_f32_32x32x16_bf16 v[64:79], v[246:249], v[222:225], v[64:79]
	ds_read_b128 v[222:225], v172 offset:4672
	s_waitcnt vmcnt(1)
	ds_write_b128 v151, v[188:191] offset:18432
	ds_write_b128 v152, v[166:169] offset:55296
	s_waitcnt lgkmcnt(11)
	v_mfma_f32_32x32x16_bf16 v[32:47], v[242:245], v[226:229], v[32:47]
	v_mfma_f32_32x32x16_bf16 v[48:63], v[246:249], v[226:229], v[48:63]
	ds_read_b128 v[226:229], v172 offset:9280
	s_waitcnt lgkmcnt(11)
	v_mfma_f32_32x32x16_bf16 v[0:15], v[242:245], v[230:233], v[0:15]
	v_mfma_f32_32x32x16_bf16 v[16:31], v[246:249], v[230:233], v[16:31]
	ds_read_b128 v[230:233], v172 offset:13888
	s_waitcnt vmcnt(0)
	ds_write_b128 v151, v[132:135] offset:27648
	ds_write_b128 v152, v[128:131] offset:64512
	s_waitcnt lgkmcnt(7)
	v_mfma_f32_32x32x16_bf16 v[112:127], v[234:237], v[218:221], v[112:127]
	ds_read_b64_tr_b16 v[242:243], v156 offset:64512
	ds_read_b64_tr_b16 v[244:245], v157 offset:29952
	ds_read_b64_tr_b16 v[246:247], v156 offset:64576
	ds_read_b64_tr_b16 v[248:249], v157 offset:30016
	v_mfma_f32_32x32x16_bf16 v[96:111], v[238:241], v[218:221], v[96:111]
	ds_read_b128 v[218:221], v172 offset:96
	v_add_co_u32_e32 v128, vcc, s29, v144
	s_nop 1
	v_addc_co_u32_e32 v129, vcc, 0, v145, vcc
	v_add_co_u32_e32 v130, vcc, s30, v144
	s_nop 1
	v_addc_co_u32_e32 v131, vcc, 0, v145, vcc
	s_waitcnt lgkmcnt(11)
	v_mfma_f32_32x32x16_bf16 v[80:95], v[234:237], v[222:225], v[80:95]
	v_mfma_f32_32x32x16_bf16 v[64:79], v[238:241], v[222:225], v[64:79]
	ds_read_b128 v[222:225], v172 offset:4704
	v_add_co_u32_e32 v132, vcc, s31, v144
	s_nop 1
	v_addc_co_u32_e32 v133, vcc, 0, v145, vcc
	v_add_co_u32_e32 v134, vcc, s34, v144
	s_nop 0
	v_addc_co_u32_e32 v135, vcc, 0, v145, vcc
	s_waitcnt lgkmcnt(9)
	v_mfma_f32_32x32x16_bf16 v[32:47], v[234:237], v[226:229], v[32:47]
	v_mfma_f32_32x32x16_bf16 v[48:63], v[238:241], v[226:229], v[48:63]
	ds_read_b128 v[226:229], v172 offset:9312
	global_load_dwordx4 v[152:155], v[136:137], off offset:1920
	global_load_dwordx4 v[158:161], v[128:129], off
	s_waitcnt lgkmcnt(9)
	v_mfma_f32_32x32x16_bf16 v[0:15], v[234:237], v[230:233], v[0:15]
	v_mfma_f32_32x32x16_bf16 v[16:31], v[238:241], v[230:233], v[16:31]
	ds_read_b128 v[230:233], v172 offset:13920
	s_nop 0
	global_load_dwordx4 v[136:139], v[138:139], off offset:1920
	s_nop 0
	global_load_dwordx4 v[162:165], v[130:131], off
	s_waitcnt lgkmcnt(3)
	v_mfma_f32_32x32x16_bf16 v[112:127], v[242:245], v[218:221], v[112:127]
	v_mfma_f32_32x32x16_bf16 v[96:111], v[246:249], v[218:221], v[96:111]
	global_load_dwordx4 v[166:169], v[140:141], off offset:1920
	s_nop 0
	global_load_dwordx4 v[128:131], v[142:143], off offset:1920
	s_waitcnt lgkmcnt(2)
	v_mfma_f32_32x32x16_bf16 v[80:95], v[242:245], v[222:225], v[80:95]
	v_mfma_f32_32x32x16_bf16 v[64:79], v[246:249], v[222:225], v[64:79]
	s_nop 0
	global_load_dwordx4 v[140:143], v[132:133], off
	s_nop 0
	global_load_dwordx4 v[132:135], v[134:135], off
	s_waitcnt lgkmcnt(0)
	s_barrier
; DI f32x16 mfma32(bf16x8 a, bf16x8 b, f32x16 c) { return __builtin_amdgcn_mfma_f32_32x32x16_bf16(a, b, c, 0, 0, 0); }
; DI s16x4 tr_read(const char* p) { bfx4 r = __builtin_amdgcn_ds_read_tr16_b64_v4bf16((LDS_AS bfx4*)p); return __builtin_bit_cast(s16x4, r); }
; DI bf16x8 cat8(s16x4 lo, s16x4 hi) { return __builtin_shufflevector(lo, hi, 0, 1, 2, 3, 4, 5, 6, 7); }
; template <int BM, class Epi>
; DI void gemm_tile(const bf16_t* __restrict__ A, int lda, const bf16_t* __restrict__ B, int ldb, int K, int row0, int col0, const Epi& epi, char* smem) {
;     ...
;     for (int kt = 0; kt < nk; ++kt) {
;         const char* cur = smem + (kt & 1) * GSTAGE;
;         char* nxt = smem + ((kt & 1) ^ 1) * GSTAGE;
;         const bool w1 = kt + 1 < nk, l2 = kt + 2 < nk;
;         const bf16_t* a2 = ag + (size_t)(kt + 2) * 64; const bf16_t* b2 = bg + (size_t)(kt + 2) * 64 * ldb;
; #pragma unroll
;         for (int s = 0; s < 4; ++s) {
;             bf16x8 xf[MI], wf[2];
; #pragma unroll
;             for (int mi = 0; mi < MI; ++mi) xf[mi] = *(const bf16x8*)(cur + xoff + mi * 32 * GA_S + s * 32);
; #pragma unroll
;             for (int ni = 0; ni < 2; ++ni) {
;                 const char* wp = cur + woff + s * 16 * GB_S + ni * 64;
;                 wf[ni] = cat8(tr_read(wp), tr_read(wp + 4 * GB_S));
;             }
; #pragma unroll
;             for (int mi = 0; mi < MI; ++mi)
; #pragma unroll
;                 for (int ni = 0; ni < 2; ++ni) acc[mi][ni] = mfma32(wf[ni], xf[mi], acc[mi][ni]);
;             if (w1) {
;                 if (s < NA_) *(u32x4*)(nxt + aw + 64 * s * GA_S) = ra[s];
;                 *(u32x4*)(nxt + bw + 16 * s * GB_S) = rb[s];
;             }
;             if (l2) {
;                 if (s < NA_) ra[s] = *(const u32x4*)(a2 + (size_t)(64 * s) * lda);
;                 rb[s] = *(const u32x4*)(b2 + (size_t)(16 * s) * ldb);
;             }
;         }
	v_mfma_f32_32x32x16_bf16 v[32:47], v[242:245], v[226:229], v[32:47]
	v_mfma_f32_32x32x16_bf16 v[48:63], v[246:249], v[226:229], v[48:63]
	v_mfma_f32_32x32x16_bf16 v[0:15], v[242:245], v[230:233], v[0:15]
	v_mfma_f32_32x32x16_bf16 v[16:31], v[246:249], v[230:233], v[16:31]
	ds_read_b64_tr_b16 v[180:181], v149 offset:36864
	ds_read_b64_tr_b16 v[182:183], v149 offset:39168
	ds_read_b64_tr_b16 v[186:187], v149 offset:39232
	ds_read_b64_tr_b16 v[184:185], v149 offset:36928
	ds_read_b128 v[188:191], v148
	ds_read_b128 v[218:221], v148 offset:4608
	s_waitcnt lgkmcnt(1)
	v_mfma_f32_32x32x16_bf16 v[112:127], v[180:183], v[188:191], v[112:127]
	v_mfma_f32_32x32x16_bf16 v[96:111], v[184:187], v[188:191], v[96:111]
	s_waitcnt lgkmcnt(0)
	v_mfma_f32_32x32x16_bf16 v[80:95], v[180:183], v[218:221], v[80:95]
	v_mfma_f32_32x32x16_bf16 v[64:79], v[184:187], v[218:221], v[64:79]
	ds_read_b128 v[188:191], v148 offset:9216
	ds_read_b128 v[218:221], v148 offset:13824
	s_waitcnt vmcnt(7)
	ds_write_b128 v147, v[152:155]
	s_waitcnt vmcnt(6)
	ds_write_b128 v146, v[158:161] offset:36864
	s_waitcnt lgkmcnt(3)
	v_mfma_f32_32x32x16_bf16 v[32:47], v[180:183], v[188:191], v[32:47]
	v_mfma_f32_32x32x16_bf16 v[48:63], v[184:187], v[188:191], v[48:63]
	s_waitcnt lgkmcnt(2)
	v_mfma_f32_32x32x16_bf16 v[0:15], v[180:183], v[218:221], v[0:15]
	v_mfma_f32_32x32x16_bf16 v[16:31], v[184:187], v[218:221], v[16:31]
	ds_read_b64_tr_b16 v[152:153], v149 offset:46080
	ds_read_b64_tr_b16 v[154:155], v149 offset:48384
	ds_read_b64_tr_b16 v[160:161], v149 offset:48448
	ds_read_b64_tr_b16 v[158:159], v149 offset:46144
	ds_read_b128 v[180:183], v148 offset:32
	ds_read_b128 v[184:187], v148 offset:4640
	s_waitcnt lgkmcnt(1)
	v_mfma_f32_32x32x16_bf16 v[112:127], v[152:155], v[180:183], v[112:127]
	v_mfma_f32_32x32x16_bf16 v[96:111], v[158:161], v[180:183], v[96:111]
	s_waitcnt lgkmcnt(0)
	v_mfma_f32_32x32x16_bf16 v[80:95], v[152:155], v[184:187], v[80:95]
	v_mfma_f32_32x32x16_bf16 v[64:79], v[158:161], v[184:187], v[64:79]
	ds_read_b128 v[180:183], v148 offset:9248
	ds_read_b128 v[184:187], v148 offset:13856
	s_waitcnt vmcnt(5)
	ds_write_b128 v147, v[136:139] offset:9216
	s_waitcnt vmcnt(4)
	ds_write_b128 v146, v[162:165] offset:46080
	s_waitcnt lgkmcnt(3)
	v_mfma_f32_32x32x16_bf16 v[32:47], v[152:155], v[180:183], v[32:47]
	v_mfma_f32_32x32x16_bf16 v[48:63], v[158:161], v[180:183], v[48:63]
	s_waitcnt lgkmcnt(2)
	v_mfma_f32_32x32x16_bf16 v[0:15], v[152:155], v[184:187], v[0:15]
	v_mfma_f32_32x32x16_bf16 v[16:31], v[158:161], v[184:187], v[16:31]
	ds_read_b64_tr_b16 v[136:137], v149 offset:55296
	ds_read_b64_tr_b16 v[138:139], v149 offset:57600
	ds_read_b64_tr_b16 v[154:155], v149 offset:57664
	ds_read_b64_tr_b16 v[152:153], v149 offset:55360
	ds_read_b128 v[158:161], v148 offset:64
	ds_read_b128 v[162:165], v148 offset:4672
	s_waitcnt lgkmcnt(1)
	v_mfma_f32_32x32x16_bf16 v[112:127], v[136:139], v[158:161], v[112:127]
	v_mfma_f32_32x32x16_bf16 v[96:111], v[152:155], v[158:161], v[96:111]
	s_waitcnt lgkmcnt(0)
	v_mfma_f32_32x32x16_bf16 v[80:95], v[136:139], v[162:165], v[80:95]
	v_mfma_f32_32x32x16_bf16 v[64:79], v[152:155], v[162:165], v[64:79]
	ds_read_b128 v[158:161], v148 offset:9280
	ds_read_b128 v[162:165], v148 offset:13888
	s_waitcnt vmcnt(3)
	ds_write_b128 v147, v[166:169] offset:18432
	s_waitcnt vmcnt(1)
	ds_write_b128 v146, v[140:143] offset:55296
	s_waitcnt lgkmcnt(3)
	v_mfma_f32_32x32x16_bf16 v[32:47], v[136:139], v[158:161], v[32:47]
	v_mfma_f32_32x32x16_bf16 v[48:63], v[152:155], v[158:161], v[48:63]
	s_waitcnt lgkmcnt(2)
	v_mfma_f32_32x32x16_bf16 v[0:15], v[136:139], v[162:165], v[0:15]
	v_mfma_f32_32x32x16_bf16 v[16:31], v[152:155], v[162:165], v[16:31]
	ds_read_b64_tr_b16 v[136:137], v149 offset:64512
	ds_read_b64_tr_b16 v[138:139], v150 offset:29952
	ds_read_b64_tr_b16 v[142:143], v150 offset:30016
	ds_read_b64_tr_b16 v[140:141], v149 offset:64576
	ds_read_b128 v[150:153], v148 offset:96
	ds_read_b128 v[158:161], v148 offset:4704
	s_waitcnt lgkmcnt(1)
	v_mfma_f32_32x32x16_bf16 v[112:127], v[136:139], v[150:153], v[112:127]
	v_mfma_f32_32x32x16_bf16 v[96:111], v[140:143], v[150:153], v[96:111]
	s_waitcnt lgkmcnt(0)
	v_mfma_f32_32x32x16_bf16 v[80:95], v[136:139], v[158:161], v[80:95]
	v_mfma_f32_32x32x16_bf16 v[64:79], v[140:143], v[158:161], v[64:79]
	ds_read_b128 v[150:153], v148 offset:9312
	ds_read_b128 v[158:161], v148 offset:13920
	ds_write_b128 v147, v[128:131] offset:27648
	s_waitcnt vmcnt(0)
	ds_write_b128 v146, v[132:135] offset:64512
	s_waitcnt lgkmcnt(0)
	s_barrier
; DI unsigned pk2(float a, float b) { f32x2 v = {a, b}; bfx2 r = __builtin_convertvector(v, bfx2); return __builtin_bit_cast(unsigned, r); }
; DI float silu_f(float x) { return x * __builtin_amdgcn_rcpf(1.f + __expf(-x)); }
; DI f32x16 mfma32(bf16x8 a, bf16x8 b, f32x16 c) { return __builtin_amdgcn_mfma_f32_32x32x16_bf16(a, b, c, 0, 0, 0); }
; DI s16x4 tr_read(const char* p) { bfx4 r = __builtin_amdgcn_ds_read_tr16_b64_v4bf16((LDS_AS bfx4*)p); return __builtin_bit_cast(s16x4, r); }
; DI bf16x8 cat8(s16x4 lo, s16x4 hi) { return __builtin_shufflevector(lo, hi, 0, 1, 2, 3, 4, 5, 6, 7); }
; template <int BM, class Epi>
; DI void gemm_tile(const bf16_t* __restrict__ A, int lda, const bf16_t* __restrict__ B, int ldb, int K, int row0, int col0, const Epi& epi, char* smem) {
;     ...
;         for (int s = 0; s < 4; ++s) {
;             bf16x8 xf[MI], wf[2];
; #pragma unroll
;             for (int mi = 0; mi < MI; ++mi) xf[mi] = *(const bf16x8*)(cur + xoff + mi * 32 * GA_S + s * 32);
; #pragma unroll
;             for (int ni = 0; ni < 2; ++ni) {
;                 const char* wp = cur + woff + s * 16 * GB_S + ni * 64;
;                 wf[ni] = cat8(tr_read(wp), tr_read(wp + 4 * GB_S));
;             }
; #pragma unroll
;             for (int mi = 0; mi < MI; ++mi)
; #pragma unroll
;                 for (int ni = 0; ni < 2; ++ni) acc[mi][ni] = mfma32(wf[ni], xf[mi], acc[mi][ni]);
;     DI void operator()(const f32x16& a0, const f32x16& a1, int row, int cbase, int hh) const {
;         bf16_t* dst = hid + (size_t)row * DFF + (cbase >> 1) + 4 * hh;
; #pragma unroll
;         for (int q4 = 0; q4 < 4; ++q4) {
;             float h[4];
; #pragma unroll
;             for (int j = 0; j < 4; ++j) h[j] = silu_f(a0[4 * q4 + j]) * a1[4 * q4 + j];
;             u32x2 w; w.x = pk2(h[0], h[1]); w.y = pk2(h[2], h[3]);
;             *(u32x2*)(dst + 8 * q4) = w;
	v_mfma_f32_32x32x16_bf16 v[32:47], v[136:139], v[150:153], v[32:47]
	v_mfma_f32_32x32x16_bf16 v[48:63], v[140:143], v[150:153], v[48:63]
	v_mfma_f32_32x32x16_bf16 v[0:15], v[136:139], v[158:161], v[0:15]
	ds_read_b64_tr_b16 v[136:137], v156 offset:36864
	ds_read_b64_tr_b16 v[138:139], v156 offset:39168
	ds_read_b64_tr_b16 v[134:135], v156 offset:39232
	ds_read_b64_tr_b16 v[132:133], v156 offset:36928
	ds_read_b128 v[128:131], v172
	ds_read_b128 v[148:151], v172 offset:32
	s_waitcnt lgkmcnt(1)
	v_mfma_f32_32x32x16_bf16 v[112:127], v[136:139], v[128:131], v[112:127]
	v_mfma_f32_32x32x16_bf16 v[96:111], v[132:135], v[128:131], v[96:111]
	ds_read_b128 v[128:131], v172 offset:4608
	ds_read_b128 v[152:155], v172 offset:4640
	s_waitcnt lgkmcnt(1)
	v_mfma_f32_32x32x16_bf16 v[80:95], v[136:139], v[128:131], v[80:95]
	v_mfma_f32_32x32x16_bf16 v[64:79], v[132:135], v[128:131], v[64:79]
	ds_read_b128 v[128:131], v172 offset:9216
	ds_read_b128 v[164:167], v172 offset:9248
	v_mfma_f32_32x32x16_bf16 v[16:31], v[140:143], v[158:161], v[16:31]
	s_waitcnt lgkmcnt(1)
	v_mfma_f32_32x32x16_bf16 v[32:47], v[136:139], v[128:131], v[32:47]
	v_mfma_f32_32x32x16_bf16 v[48:63], v[132:135], v[128:131], v[48:63]
	ds_read_b128 v[140:143], v172 offset:13824
	ds_read_b128 v[128:131], v172 offset:13856
	s_waitcnt lgkmcnt(1)
	v_mfma_f32_32x32x16_bf16 v[0:15], v[136:139], v[140:143], v[0:15]
	ds_read_b64_tr_b16 v[144:145], v156 offset:46080
	ds_read_b64_tr_b16 v[146:147], v156 offset:48384
	ds_read_b64_tr_b16 v[138:139], v156 offset:48448
	ds_read_b64_tr_b16 v[136:137], v156 offset:46144
	s_waitcnt lgkmcnt(2)
	v_mfma_f32_32x32x16_bf16 v[112:127], v[144:147], v[148:151], v[112:127]
	s_waitcnt lgkmcnt(0)
	v_mfma_f32_32x32x16_bf16 v[96:111], v[136:139], v[148:151], v[96:111]
	v_mfma_f32_32x32x16_bf16 v[80:95], v[144:147], v[152:155], v[80:95]
	v_mfma_f32_32x32x16_bf16 v[64:79], v[136:139], v[152:155], v[64:79]
	ds_read_b64_tr_b16 v[152:153], v156 offset:55296
	ds_read_b64_tr_b16 v[154:155], v156 offset:57600
	ds_read_b64_tr_b16 v[150:151], v156 offset:57664
	ds_read_b64_tr_b16 v[148:149], v156 offset:55360
	ds_read_b128 v[158:161], v172 offset:64
	ds_read_b128 v[180:183], v172 offset:96
	s_waitcnt lgkmcnt(1)
	v_mfma_f32_32x32x16_bf16 v[112:127], v[152:155], v[158:161], v[112:127]
	v_mfma_f32_32x32x16_bf16 v[96:111], v[148:151], v[158:161], v[96:111]
	ds_read_b128 v[158:161], v172 offset:4672
	ds_read_b128 v[168:171], v172 offset:4704
	s_waitcnt lgkmcnt(1)
	v_mfma_f32_32x32x16_bf16 v[80:95], v[152:155], v[158:161], v[80:95]
	v_mfma_f32_32x32x16_bf16 v[64:79], v[148:151], v[158:161], v[64:79]
	ds_read_b64_tr_b16 v[160:161], v156 offset:64512
	ds_read_b64_tr_b16 v[162:163], v157 offset:29952
	ds_read_b64_tr_b16 v[158:159], v157 offset:30016
	ds_read_b64_tr_b16 v[156:157], v156 offset:64576
	s_waitcnt lgkmcnt(2)
	v_mfma_f32_32x32x16_bf16 v[112:127], v[160:163], v[180:183], v[112:127]
	s_waitcnt lgkmcnt(0)
	v_mfma_f32_32x32x16_bf16 v[96:111], v[156:159], v[180:183], v[96:111]
	s_nop 9
	v_mul_f32_e32 v182, 0xbfb8aa3b, v114
	v_mul_f32_e32 v183, 0xbfb8aa3b, v115
	v_mul_f32_e32 v188, 0xbfb8aa3b, v120
	v_mul_f32_e32 v189, 0xbfb8aa3b, v121
	v_mul_f32_e32 v180, 0xbfb8aa3b, v112
	v_mul_f32_e32 v181, 0xbfb8aa3b, v113
	v_exp_f32_e32 v182, v182
	v_exp_f32_e32 v183, v183
	v_mul_f32_e32 v184, 0xbfb8aa3b, v116
	v_mul_f32_e32 v185, 0xbfb8aa3b, v117
	v_mul_f32_e32 v186, 0xbfb8aa3b, v118
	v_mul_f32_e32 v187, 0xbfb8aa3b, v119
	v_exp_f32_e32 v188, v188
	v_exp_f32_e32 v189, v189
	v_mul_f32_e32 v190, 0xbfb8aa3b, v122
	v_mul_f32_e32 v191, 0xbfb8aa3b, v123
	v_mul_f32_e32 v192, 0xbfb8aa3b, v124
	v_mul_f32_e32 v193, 0xbfb8aa3b, v125
	v_mul_f32_e32 v217, 0xbfb8aa3b, v126
	v_mul_f32_e32 v218, 0xbfb8aa3b, v127
	v_exp_f32_e32 v180, v180
	v_exp_f32_e32 v181, v181
	v_exp_f32_e32 v184, v184
	v_exp_f32_e32 v185, v185
	v_exp_f32_e32 v186, v186
	v_exp_f32_e32 v187, v187
	v_exp_f32_e32 v190, v190
	v_exp_f32_e32 v191, v191
	v_exp_f32_e32 v192, v192
	v_exp_f32_e32 v193, v193
	v_exp_f32_e32 v217, v217
	v_exp_f32_e32 v218, v218
	v_mfma_f32_32x32x16_bf16 v[80:95], v[160:163], v[168:171], v[80:95]
	v_add_f32_e32 v182, 1.0, v182
	v_add_f32_e32 v183, 1.0, v183
	v_add_f32_e32 v188, 1.0, v188
	v_add_f32_e32 v189, 1.0, v189
	v_add_f32_e32 v180, 1.0, v180
	v_add_f32_e32 v181, 1.0, v181
	v_rcp_f32_e32 v182, v182
	v_rcp_f32_e32 v183, v183
	v_add_f32_e32 v184, 1.0, v184
	v_add_f32_e32 v185, 1.0, v185
	v_add_f32_e32 v186, 1.0, v186
	v_add_f32_e32 v187, 1.0, v187
	v_rcp_f32_e32 v188, v188
	v_rcp_f32_e32 v189, v189
	v_add_f32_e32 v190, 1.0, v190
	v_add_f32_e32 v191, 1.0, v191
	v_add_f32_e32 v192, 1.0, v192
	v_add_f32_e32 v193, 1.0, v193
	v_add_f32_e32 v217, 1.0, v217
	v_add_f32_e32 v219, 1.0, v218
	v_rcp_f32_e32 v180, v180
	v_rcp_f32_e32 v181, v181
	v_rcp_f32_e32 v184, v184
	v_rcp_f32_e32 v185, v185
	v_rcp_f32_e32 v186, v186
	v_rcp_f32_e32 v187, v187
	v_rcp_f32_e32 v190, v190
	v_rcp_f32_e32 v191, v191
	v_rcp_f32_e32 v192, v192
	v_rcp_f32_e32 v193, v193
	v_rcp_f32_e32 v218, v217
	v_rcp_f32_e32 v219, v219
	v_pk_mul_f32 v[114:115], v[114:115], v[182:183]
	v_pk_mul_f32 v[120:121], v[120:121], v[188:189]
	v_pk_mul_f32 v[112:113], v[112:113], v[180:181]
	v_pk_mul_f32 v[180:181], v[116:117], v[184:185]
	v_pk_mul_f32 v[182:183], v[118:119], v[186:187]
	v_pk_mul_f32 v[122:123], v[122:123], v[190:191]
	v_pk_mul_f32 v[124:125], v[124:125], v[192:193]
	v_pk_mul_f32 v[126:127], v[126:127], v[218:219]
	v_pk_mul_f32 v[118:119], v[98:99], v[114:115]
	v_pk_mul_f32 v[98:99], v[104:105], v[120:121]
	v_mul_f32_e32 v104, 0xbfb8aa3b, v80
	v_mul_f32_e32 v105, 0xbfb8aa3b, v81
	v_pk_mul_f32 v[116:117], v[96:97], v[112:113]
	v_pk_mul_f32 v[112:113], v[100:101], v[180:181]
; DI unsigned pk2(float a, float b) { f32x2 v = {a, b}; bfx2 r = __builtin_convertvector(v, bfx2); return __builtin_bit_cast(unsigned, r); }
; DI float silu_f(float x) { return x * __builtin_amdgcn_rcpf(1.f + __expf(-x)); }
;     DI void operator()(const f32x16& a0, const f32x16& a1, int row, int cbase, int hh) const {
;         bf16_t* dst = hid + (size_t)row * DFF + (cbase >> 1) + 4 * hh;
; #pragma unroll
;         for (int q4 = 0; q4 < 4; ++q4) {
;             float h[4];
; #pragma unroll
;             for (int j = 0; j < 4; ++j) h[j] = silu_f(a0[4 * q4 + j]) * a1[4 * q4 + j];
;             u32x2 w; w.x = pk2(h[0], h[1]); w.y = pk2(h[2], h[3]);
;             *(u32x2*)(dst + 8 * q4) = w;
;         }
	v_pk_mul_f32 v[114:115], v[102:103], v[182:183]
	v_pk_mul_f32 v[100:101], v[106:107], v[122:123]
	v_pk_mul_f32 v[96:97], v[108:109], v[124:125]
	v_pk_mul_f32 v[102:103], v[110:111], v[126:127]
	v_exp_f32_e32 v104, v104
	v_exp_f32_e32 v105, v105
	v_mul_f32_e32 v106, 0xbfb8aa3b, v82
	v_mul_f32_e32 v107, 0xbfb8aa3b, v83
	v_mul_f32_e32 v108, 0xbfb8aa3b, v84
	v_mul_f32_e32 v109, 0xbfb8aa3b, v85
	v_mul_f32_e32 v110, 0xbfb8aa3b, v86
	v_mul_f32_e32 v111, 0xbfb8aa3b, v87
	v_mul_f32_e32 v124, 0xbfb8aa3b, v92
	v_mul_f32_e32 v125, 0xbfb8aa3b, v93
	v_mul_f32_e32 v126, 0xbfb8aa3b, v94
	v_mul_f32_e32 v127, 0xbfb8aa3b, v95
	v_exp_f32_e32 v106, v106
	v_exp_f32_e32 v107, v107
	v_exp_f32_e32 v108, v108
	v_exp_f32_e32 v109, v109
	v_exp_f32_e32 v110, v110
	v_exp_f32_e32 v111, v111
	v_exp_f32_e32 v124, v124
	v_exp_f32_e32 v125, v125
	v_exp_f32_e32 v126, v126
	v_exp_f32_e32 v127, v127
	v_mfma_f32_32x32x16_bf16 v[64:79], v[156:159], v[168:171], v[64:79]
	v_add_f32_e32 v104, 1.0, v104
	v_add_f32_e32 v105, 1.0, v105
	v_rcp_f32_e32 v104, v104
	v_rcp_f32_e32 v105, v105
	v_add_f32_e32 v106, 1.0, v106
	v_add_f32_e32 v107, 1.0, v107
	v_add_f32_e32 v108, 1.0, v108
	v_add_f32_e32 v109, 1.0, v109
	v_add_f32_e32 v110, 1.0, v110
	v_add_f32_e32 v111, 1.0, v111
	v_add_f32_e32 v124, 1.0, v124
	v_add_f32_e32 v125, 1.0, v125
	v_add_f32_e32 v126, 1.0, v126
	v_add_f32_e32 v127, 1.0, v127
	v_mfma_f32_32x32x16_bf16 v[32:47], v[144:147], v[164:167], v[32:47]
	v_rcp_f32_e32 v106, v106
	v_rcp_f32_e32 v107, v107
	v_rcp_f32_e32 v108, v108
	v_rcp_f32_e32 v109, v109
	v_rcp_f32_e32 v110, v110
	v_rcp_f32_e32 v111, v111
	v_rcp_f32_e32 v124, v124
	v_rcp_f32_e32 v125, v125
	v_rcp_f32_e32 v126, v126
	v_rcp_f32_e32 v127, v127
	v_mul_f32_e32 v120, 0xbfb8aa3b, v88
	v_mul_f32_e32 v121, 0xbfb8aa3b, v89
	v_exp_f32_e32 v120, v120
	v_exp_f32_e32 v121, v121
	v_pk_mul_f32 v[80:81], v[80:81], v[104:105]
	v_pk_mul_f32 v[82:83], v[82:83], v[106:107]
	v_pk_mul_f32 v[84:85], v[84:85], v[108:109]
	v_pk_mul_f32 v[86:87], v[86:87], v[110:111]
	v_pk_mul_f32 v[92:93], v[92:93], v[124:125]
	v_pk_mul_f32 v[94:95], v[94:95], v[126:127]
	v_pk_mul_f32 v[104:105], v[64:65], v[80:81]
	v_or_b32_e32 v64, s0, v178
	v_mul_f32_e32 v122, 0xbfb8aa3b, v90
	v_mul_f32_e32 v123, 0xbfb8aa3b, v91
	v_pk_mul_f32 v[106:107], v[66:67], v[82:83]
	v_pk_mul_f32 v[84:85], v[68:69], v[84:85]
	v_pk_mul_f32 v[86:87], v[70:71], v[86:87]
	v_pk_mul_f32 v[92:93], v[76:77], v[92:93]
	v_pk_mul_f32 v[94:95], v[78:79], v[94:95]
	v_cvt_pk_bf16_f32 v108, v116, v117
	v_add_u32_e32 v116, v64, v179
	ds_read_b128 v[76:79], v172 offset:9280
	ds_read_b128 v[80:83], v172 offset:9312
	ds_read_b128 v[68:71], v172 offset:13888
	ds_read_b128 v[64:67], v172 offset:13920
	v_exp_f32_e32 v122, v122
	v_exp_f32_e32 v123, v123
	v_add_f32_e32 v120, 1.0, v120
	v_add_f32_e32 v121, 1.0, v121
	s_waitcnt lgkmcnt(3)
	v_mfma_f32_32x32x16_bf16 v[32:47], v[152:155], v[76:79], v[32:47]
	v_rcp_f32_e32 v120, v120
	v_rcp_f32_e32 v121, v121
	v_add_f32_e32 v122, 1.0, v122
	v_add_f32_e32 v123, 1.0, v123
	v_rcp_f32_e32 v122, v122
	v_rcp_f32_e32 v123, v123
	v_pk_mul_f32 v[88:89], v[88:89], v[120:121]
	v_mfma_f32_32x32x16_bf16 v[48:63], v[136:139], v[164:167], v[48:63]
	v_mul_f32_e64 v88, v72, v88
	v_mul_f32_e64 v89, v73, v89
	v_and_b32_e32 v72, 0xc0, v177
	v_or_b32_e32 v72, s6, v72
	v_readlane_b32 s0, v253, 3
	v_pk_mul_f32 v[90:91], v[90:91], v[122:123]
	v_ashrrev_i32_e32 v72, 1, v72
	v_readlane_b32 s1, v253, 4
	s_waitcnt lgkmcnt(2)
	v_mfma_f32_32x32x16_bf16 v[32:47], v[160:163], v[80:83], v[32:47]
	v_mul_f32_e64 v90, v74, v90
	v_mul_f32_e64 v91, v75, v91
	v_ashrrev_i32_e32 v73, 31, v72
	v_mov_b64_e32 v[74:75], s[0:1]
	v_lshlrev_b64 v[72:73], 1, v[72:73]
	v_mov_b32_e32 v177, v173
	s_waitcnt lgkmcnt(0)
	s_barrier
	v_mfma_f32_32x32x16_bf16 v[48:63], v[148:151], v[76:79], v[48:63]
	v_or_b32_e32 v78, 32, v116
	v_mad_i64_i32 v[78:79], s[0:1], v78, s27, v[74:75]
	v_lshl_add_u64 v[78:79], v[78:79], 0, v[72:73]
	v_cvt_pk_bf16_f32 v76, v104, v105
	v_cvt_pk_bf16_f32 v77, v106, v107
	v_lshl_add_u64 v[78:79], v[78:79], 0, v[176:177]
	global_store_dwordx2 v[78:79], v[76:77], off
	v_cvt_pk_bf16_f32 v76, v84, v85
	v_cvt_pk_bf16_f32 v77, v86, v87
	global_store_dwordx2 v[78:79], v[76:77], off offset:16
	v_cvt_pk_bf16_f32 v76, v88, v89
	v_cvt_pk_bf16_f32 v77, v90, v91
	global_store_dwordx2 v[78:79], v[76:77], off offset:32
	v_cvt_pk_bf16_f32 v76, v92, v93
	v_cvt_pk_bf16_f32 v77, v94, v95
	global_store_dwordx2 v[78:79], v[76:77], off offset:48
	v_mul_f32_e32 v76, 0xbfb8aa3b, v32
	v_mul_f32_e32 v77, 0xbfb8aa3b, v33
	v_mul_f32_e32 v78, 0xbfb8aa3b, v34
	v_mul_f32_e32 v79, 0xbfb8aa3b, v35
	v_exp_f32_e32 v76, v76
	v_exp_f32_e32 v77, v77
	v_exp_f32_e32 v78, v78
	v_exp_f32_e32 v79, v79
	v_mfma_f32_32x32x16_bf16 v[48:63], v[156:159], v[80:83], v[48:63]
	v_add_f32_e32 v76, 1.0, v76
	v_add_f32_e32 v77, 1.0, v77
	v_add_f32_e32 v78, 1.0, v78
	v_add_f32_e32 v79, 1.0, v79
	v_rcp_f32_e32 v76, v76
	v_rcp_f32_e32 v77, v77
	v_rcp_f32_e32 v78, v78
	v_rcp_f32_e32 v79, v79
	v_mfma_f32_32x32x16_bf16 v[0:15], v[144:147], v[128:131], v[0:15]
	v_mul_f32_e64 v32, v32, v76
	v_mul_f32_e64 v33, v33, v77
	v_mad_i64_i32 v[110:111], s[0:1], v116, s27, v[74:75]
	v_mul_f32_e64 v34, v34, v78
	v_mul_f32_e64 v35, v35, v79
	v_pk_mul_f32 v[32:33], v[48:49], v[32:33]
	v_pk_mul_f32 v[34:35], v[50:51], v[34:35]
	v_cvt_pk_bf16_f32 v32, v32, v33
	v_cvt_pk_bf16_f32 v33, v34, v35
	v_or_b32_e32 v34, 64, v116
	v_mad_i64_i32 v[34:35], s[0:1], v34, s27, v[74:75]
	v_lshl_add_u64 v[34:35], v[34:35], 0, v[72:73]
	v_lshl_add_u64 v[34:35], v[34:35], 0, v[176:177]
	global_store_dwordx2 v[34:35], v[32:33], off
	v_mul_f32_e32 v32, 0xbfb8aa3b, v36
; DI unsigned pk2(float a, float b) { f32x2 v = {a, b}; bfx2 r = __builtin_convertvector(v, bfx2); return __builtin_bit_cast(unsigned, r); }
; DI float silu_f(float x) { return x * __builtin_amdgcn_rcpf(1.f + __expf(-x)); }
;     DI void operator()(const f32x16& a0, const f32x16& a1, int row, int cbase, int hh) const {
;         bf16_t* dst = hid + (size_t)row * DFF + (cbase >> 1) + 4 * hh;
; #pragma unroll
;         for (int q4 = 0; q4 < 4; ++q4) {
;             float h[4];
; #pragma unroll
;             for (int j = 0; j < 4; ++j) h[j] = silu_f(a0[4 * q4 + j]) * a1[4 * q4 + j];
;             u32x2 w; w.x = pk2(h[0], h[1]); w.y = pk2(h[2], h[3]);
;             *(u32x2*)(dst + 8 * q4) = w;
;         }
	v_mul_f32_e32 v33, 0xbfb8aa3b, v37
	v_mul_f32_e32 v48, 0xbfb8aa3b, v38
	v_mul_f32_e32 v49, 0xbfb8aa3b, v39
	v_exp_f32_e32 v32, v32
	v_exp_f32_e32 v33, v33
	v_exp_f32_e32 v48, v48
	v_exp_f32_e32 v49, v49
	v_add_f32_e32 v32, 1.0, v32
	v_add_f32_e32 v33, 1.0, v33
	v_add_f32_e32 v48, 1.0, v48
	v_add_f32_e32 v49, 1.0, v49
	v_rcp_f32_e32 v32, v32
	v_rcp_f32_e32 v33, v33
	v_rcp_f32_e32 v48, v48
	v_rcp_f32_e32 v49, v49
	v_mfma_f32_32x32x16_bf16 v[16:31], v[132:135], v[140:143], v[16:31]
	v_mul_f32_e64 v32, v36, v32
	v_mul_f32_e64 v33, v37, v33
	v_lshl_add_u64 v[110:111], v[110:111], 0, v[72:73]
	v_mul_f32_e64 v36, v38, v48
	v_mul_f32_e64 v37, v39, v49
	v_pk_mul_f32 v[32:33], v[52:53], v[32:33]
	v_pk_mul_f32 v[36:37], v[54:55], v[36:37]
	v_cvt_pk_bf16_f32 v32, v32, v33
	v_cvt_pk_bf16_f32 v33, v36, v37
	global_store_dwordx2 v[34:35], v[32:33], off offset:16
	v_mul_f32_e32 v32, 0xbfb8aa3b, v40
	v_mul_f32_e32 v33, 0xbfb8aa3b, v41
	v_mul_f32_e32 v36, 0xbfb8aa3b, v42
	v_mul_f32_e32 v37, 0xbfb8aa3b, v43
	v_exp_f32_e32 v32, v32
	v_exp_f32_e32 v33, v33
	v_exp_f32_e32 v36, v36
	v_exp_f32_e32 v37, v37
	v_add_f32_e32 v32, 1.0, v32
	v_add_f32_e32 v33, 1.0, v33
	v_add_f32_e32 v36, 1.0, v36
	v_add_f32_e32 v37, 1.0, v37
	v_rcp_f32_e32 v32, v32
	v_rcp_f32_e32 v33, v33
	v_rcp_f32_e32 v36, v36
	v_rcp_f32_e32 v37, v37
	v_mfma_f32_32x32x16_bf16 v[0:15], v[152:155], v[68:71], v[0:15]
	v_mul_f32_e64 v32, v40, v32
	v_mul_f32_e64 v33, v41, v33
	v_cvt_pk_bf16_f32 v109, v118, v119
	v_mul_f32_e64 v36, v42, v36
	v_mul_f32_e64 v37, v43, v37
	v_pk_mul_f32 v[32:33], v[56:57], v[32:33]
	v_pk_mul_f32 v[36:37], v[58:59], v[36:37]
	v_cvt_pk_bf16_f32 v32, v32, v33
	v_cvt_pk_bf16_f32 v33, v36, v37
	v_mul_f32_e32 v36, 0xbfb8aa3b, v44
	v_mul_f32_e32 v37, 0xbfb8aa3b, v45
	v_exp_f32_e32 v36, v36
	v_exp_f32_e32 v37, v37
	global_store_dwordx2 v[34:35], v[32:33], off offset:32
	v_mfma_f32_32x32x16_bf16 v[16:31], v[136:139], v[128:131], v[16:31]
	v_add_f32_e32 v32, 1.0, v36
	v_add_f32_e32 v33, 1.0, v37
	v_mul_f32_e32 v36, 0xbfb8aa3b, v46
	v_mul_f32_e32 v37, 0xbfb8aa3b, v47
	v_exp_f32_e32 v36, v36
	v_exp_f32_e32 v37, v37
	v_rcp_f32_e32 v32, v32
	v_mfma_f32_32x32x16_bf16 v[0:15], v[160:163], v[64:67], v[0:15]
	v_add_f32_e32 v36, 1.0, v36
	v_add_f32_e32 v37, 1.0, v37
	v_rcp_f32_e32 v33, v33
	v_rcp_f32_e32 v36, v36
	v_rcp_f32_e32 v37, v37
	v_lshl_add_u64 v[110:111], v[110:111], 0, v[176:177]
	v_pk_mul_f32 v[32:33], v[44:45], v[32:33]
	v_mfma_f32_32x32x16_bf16 v[16:31], v[148:151], v[68:71], v[16:31]
	v_mul_f32_e64 v36, v46, v36
	v_mul_f32_e64 v37, v47, v37
	v_mul_f32_e64 v32, v60, v32
	v_mul_f32_e64 v33, v61, v33
	v_mul_f32_e64 v36, v62, v36
	v_mul_f32_e64 v37, v63, v37
	v_cvt_pk_bf16_f32 v32, v32, v33
	v_cvt_pk_bf16_f32 v33, v36, v37
	global_store_dwordx2 v[34:35], v[32:33], off offset:48
	v_mul_f32_e32 v34, 0xbfb8aa3b, v0
	v_mul_f32_e32 v35, 0xbfb8aa3b, v1
	v_exp_f32_e32 v34, v34
	v_exp_f32_e32 v35, v35
	v_mfma_f32_32x32x16_bf16 v[16:31], v[156:159], v[64:67], v[16:31]
	v_mul_f32_e32 v36, 0xbfb8aa3b, v2
	v_add_f32_e32 v34, 1.0, v34
	v_add_f32_e32 v35, 1.0, v35
	v_rcp_f32_e32 v34, v34
	v_rcp_f32_e32 v35, v35
	v_mul_f32_e32 v37, 0xbfb8aa3b, v3
	v_exp_f32_e32 v36, v36
	v_exp_f32_e32 v37, v37
	v_pk_mul_f32 v[0:1], v[0:1], v[34:35]
	v_or_b32_e32 v32, 0x60, v116
	v_add_f32_e32 v34, 1.0, v36
	v_add_f32_e32 v35, 1.0, v37
	v_pk_mul_f32 v[0:1], v[16:17], v[0:1]
	v_rcp_f32_e32 v34, v34
	v_rcp_f32_e32 v35, v35
	v_cvt_pk_bf16_f32 v0, v0, v1
	v_mul_f32_e32 v1, 0xbfb8aa3b, v4
	v_exp_f32_e32 v16, v1
	v_mul_f32_e32 v1, 0xbfb8aa3b, v5
	v_exp_f32_e32 v17, v1
	v_pk_mul_f32 v[2:3], v[2:3], v[34:35]
	v_mad_i64_i32 v[32:33], s[0:1], v32, s27, v[74:75]
	v_pk_mul_f32 v[2:3], v[18:19], v[2:3]
	v_lshl_add_u64 v[32:33], v[32:33], 0, v[72:73]
	v_cvt_pk_bf16_f32 v1, v2, v3
	v_add_f32_e32 v2, 1.0, v16
	v_add_f32_e32 v3, 1.0, v17
	v_rcp_f32_e32 v2, v2
	v_mul_f32_e32 v16, 0xbfb8aa3b, v6
	v_mul_f32_e32 v17, 0xbfb8aa3b, v7
	v_rcp_f32_e32 v3, v3
	v_exp_f32_e32 v16, v16
	v_exp_f32_e32 v17, v17
	v_lshl_add_u64 v[32:33], v[32:33], 0, v[176:177]
	global_store_dwordx2 v[32:33], v[0:1], off
	v_pk_mul_f32 v[0:1], v[4:5], v[2:3]
	v_add_f32_e32 v16, 1.0, v16
	v_add_f32_e32 v17, 1.0, v17
	v_pk_mul_f32 v[0:1], v[20:21], v[0:1]
	v_rcp_f32_e32 v16, v16
	v_rcp_f32_e32 v17, v17
	v_cvt_pk_bf16_f32 v0, v0, v1
	v_mul_f32_e32 v1, 0xbfb8aa3b, v8
	v_exp_f32_e32 v4, v1
	v_mul_f32_e32 v1, 0xbfb8aa3b, v9
	v_exp_f32_e32 v5, v1
	v_pk_mul_f32 v[2:3], v[6:7], v[16:17]
	global_store_dwordx2 v[110:111], v[108:109], off
	v_pk_mul_f32 v[2:3], v[22:23], v[2:3]
	v_cvt_pk_bf16_f32 v108, v112, v113
	v_cvt_pk_bf16_f32 v1, v2, v3
	v_add_f32_e32 v2, 1.0, v4
	v_add_f32_e32 v3, 1.0, v5
	v_mul_f32_e32 v4, 0xbfb8aa3b, v10
	v_mul_f32_e32 v5, 0xbfb8aa3b, v11
	v_exp_f32_e32 v4, v4
	v_exp_f32_e32 v5, v5
	v_rcp_f32_e32 v2, v2
	v_rcp_f32_e32 v3, v3
	v_add_f32_e32 v4, 1.0, v4
	v_add_f32_e32 v5, 1.0, v5
	v_rcp_f32_e32 v4, v4
	v_rcp_f32_e32 v5, v5
	global_store_dwordx2 v[32:33], v[0:1], off offset:16
	v_pk_mul_f32 v[0:1], v[8:9], v[2:3]
	v_cvt_pk_bf16_f32 v109, v114, v115
	v_pk_mul_f32 v[0:1], v[24:25], v[0:1]
	v_pk_mul_f32 v[2:3], v[10:11], v[4:5]
	v_cvt_pk_bf16_f32 v0, v0, v1
	v_mul_f32_e32 v1, 0xbfb8aa3b, v12
	v_exp_f32_e32 v4, v1
	v_mul_f32_e32 v1, 0xbfb8aa3b, v13
	v_exp_f32_e32 v5, v1
	v_pk_mul_f32 v[2:3], v[26:27], v[2:3]
	v_cvt_pk_bf16_f32 v98, v98, v99
	v_cvt_pk_bf16_f32 v1, v2, v3
	v_add_f32_e32 v2, 1.0, v4
	v_add_f32_e32 v3, 1.0, v5
	v_mul_f32_e32 v4, 0xbfb8aa3b, v14
	v_mul_f32_e32 v5, 0xbfb8aa3b, v15
	v_exp_f32_e32 v4, v4
	v_exp_f32_e32 v5, v5
	v_rcp_f32_e32 v2, v2
	v_rcp_f32_e32 v3, v3
	v_add_f32_e32 v4, 1.0, v4
	v_add_f32_e32 v5, 1.0, v5
	v_rcp_f32_e32 v4, v4
	v_rcp_f32_e32 v5, v5
	global_store_dwordx2 v[32:33], v[0:1], off offset:32
	v_pk_mul_f32 v[0:1], v[12:13], v[2:3]
	v_cvt_pk_bf16_f32 v99, v100, v101
	v_pk_mul_f32 v[2:3], v[14:15], v[4:5]
	v_pk_mul_f32 v[0:1], v[28:29], v[0:1]
	v_pk_mul_f32 v[2:3], v[30:31], v[2:3]
	v_cvt_pk_bf16_f32 v96, v96, v97
	v_cvt_pk_bf16_f32 v97, v102, v103
	v_cvt_pk_bf16_f32 v0, v0, v1
	v_cvt_pk_bf16_f32 v1, v2, v3
	global_store_dwordx2 v[110:111], v[108:109], off offset:16
	global_store_dwordx2 v[110:111], v[98:99], off offset:32
	global_store_dwordx2 v[110:111], v[96:97], off offset:48
	global_store_dwordx2 v[32:33], v[0:1], off offset:48
	s_cbranch_scc1 .LBB0_1510
